# GEMM K-loops: A-half staging moved one segment later so LDS-DMA pieces per segment are 2/4/4/6 instead of 2/6/2/6 (counted wait 6 after the 4-piece segment)
# speedup vs baseline: 1.0030x; 1.0018x over previous
; #define PG8_STAGE(bufoff, gbase, voff) do { _Pragma("unroll") for (int _i = 0; _i < 2; ++_i) \
;         __builtin_amdgcn_global_load_lds((const unsigned*)((const char*)(gbase) + (voff)[_i]), (PG8_LAS unsigned*)(lds + (bufoff) + ldsw + _i * 8192), 16, 0, 0); } while (0)
; #define PG8_LDA(dst, b, h) do { _Pragma("unroll") for (int m = 0; m < 4; ++m) _Pragma("unroll") for (int k = 0; k < 2; ++k) dst[m][k] = *(const PG8_LAS bf16x8*)(lds + PG8_SA(b, h) + aoff + m * 2048 + k * 1024); } while (0)
; #define PG8_LDB(dst, b, h) do { _Pragma("unroll") for (int n = 0; n < 2; ++n) _Pragma("unroll") for (int k = 0; k < 2; ++k) dst[n][k] = *(const PG8_LAS bf16x8*)(lds + PG8_SB(b, h) + boff + n * 2048 + k * 1024); } while (0)
; #define PG8_MMA(ai, bj, At, Bt) do { __builtin_amdgcn_s_setprio(1); _Pragma("unroll") for (int m = 0; m < 4; ++m) _Pragma("unroll") for (int n = 0; n < 2; ++n) _Pragma("unroll") for (int k = 0; k < 2; ++k) \
;         acc[ai][bj][m][n] = __builtin_amdgcn_mfma_f32_16x16x32_bf16(Bt[n][k], At[m][k], acc[ai][bj][m][n], 0, 0, 0); __builtin_amdgcn_s_setprio(0); } while (0)
; #define PG8_WAIT_V(n) asm volatile("s_waitcnt vmcnt(" #n ")" ::: "memory")
; #define PG8_WAIT_L(n) asm volatile("s_waitcnt lgkmcnt(" #n ")" ::: "memory")
; #define PG8_BAR __builtin_amdgcn_s_barrier()
; #define PG8_SCHED __builtin_amdgcn_sched_barrier(0)
; template <class Epi, class Sched, bool ALIGN_EPI = false, bool SP2 = false>
; __device__ __forceinline__ void gemm_phase(PG8_LAS unsigned char* lds, const Gemm g, const Sched& S, const Epi& E) {
;     ...
;             PG8_LDB(B0, 0, 0); PG8_LDB(B1, 0, 1); PG8_SCHED; PG8_LDA(At, 0, 0); PG8_STAGE(PG8_SA(1, 1), a1 + hstep, voffA);
;             PG8_WAIT_V(8); PG8_WAIT_L(0); PG8_BAR; PG8_MMA(0, 0, At, B0); PG8_MMA(0, 1, At, B1); PG8_BAR; PG8_SCHED;
;             PG8_LDA(At, 0, 1); PG8_STAGE(PG8_SB(0, 0), b2, voffB); PG8_STAGE(PG8_SB(0, 1), b2 + hstep, voffB); PG8_STAGE(PG8_SA(0, 0), a2, voffA);
;             PG8_WAIT_V(8); PG8_WAIT_L(0); PG8_BAR; PG8_MMA(1, 0, At, B0); PG8_MMA(1, 1, At, B1); PG8_BAR; PG8_SCHED;
.LBB0_134:
	ds_read_b128 v[146:149], v152
	ds_read_b128 v[158:161], v152 offset:1024
	ds_read_b128 v[162:165], v152 offset:2048
	ds_read_b128 v[170:173], v152 offset:3072
	ds_read_b128 v[174:177], v153
	ds_read_b128 v[180:183], v153 offset:1024
	ds_read_b128 v[184:187], v153 offset:2048
	ds_read_b128 v[192:195], v153 offset:3072
	s_add_u32 s24, s22, 0xfff80080
	s_addc_u32 s25, s23, -1
	s_cmp_eq_u32 s62, 28
	s_cselect_b32 s27, s15, s25
	s_cselect_b32 s26, s58, s24
	s_cselect_b32 s25, s13, s61
	s_cselect_b32 s24, s59, s60
	v_lshl_add_u64 v[166:167], s[22:23], 0, v[136:137]
	s_add_i32 m0, s21, 0xc000
	ds_read_b128 v[196:199], v154
	ds_read_b128 v[200:203], v154 offset:1024
	ds_read_b128 v[204:207], v154 offset:2048
	ds_read_b128 v[208:211], v154 offset:3072
	ds_read_b128 v[212:215], v154 offset:4096
	ds_read_b128 v[216:219], v154 offset:5120
	ds_read_b128 v[220:223], v154 offset:6144
	ds_read_b128 v[224:227], v154 offset:7168
	global_load_lds_dwordx4 v[166:167], off
	v_lshl_add_u64 v[166:167], s[22:23], 0, v[138:139]
	s_add_i32 m0, s21, 0xe000
	s_nop 0
	global_load_lds_dwordx4 v[166:167], off
	s_waitcnt vmcnt(8)
	s_waitcnt lgkmcnt(0)
	s_barrier
	s_setprio 1
	s_waitcnt lgkmcnt(0)
	v_mfma_f32_16x16x32_bf16 v[124:127], v[146:149], v[196:199], v[124:127]
	v_mfma_f32_16x16x32_bf16 v[120:123], v[162:165], v[196:199], v[120:123]
	v_mfma_f32_16x16x32_bf16 v[112:115], v[146:149], v[204:207], v[112:115]
	v_mfma_f32_16x16x32_bf16 v[104:107], v[162:165], v[204:207], v[104:107]
	v_mfma_f32_16x16x32_bf16 v[96:99], v[146:149], v[212:215], v[96:99]
	v_mfma_f32_16x16x32_bf16 v[88:91], v[162:165], v[212:215], v[88:91]
	v_mfma_f32_16x16x32_bf16 v[80:83], v[146:149], v[220:223], v[80:83]
	v_mfma_f32_16x16x32_bf16 v[72:75], v[162:165], v[220:223], v[72:75]
	v_mfma_f32_16x16x32_bf16 v[124:127], v[158:161], v[200:203], v[124:127]
	v_mfma_f32_16x16x32_bf16 v[120:123], v[170:173], v[200:203], v[120:123]
	v_mfma_f32_16x16x32_bf16 v[112:115], v[158:161], v[208:211], v[112:115]
	v_mfma_f32_16x16x32_bf16 v[104:107], v[170:173], v[208:211], v[104:107]
	v_mfma_f32_16x16x32_bf16 v[96:99], v[158:161], v[216:219], v[96:99]
	v_mfma_f32_16x16x32_bf16 v[88:91], v[170:173], v[216:219], v[88:91]
	v_mfma_f32_16x16x32_bf16 v[80:83], v[158:161], v[224:227], v[80:83]
	v_mfma_f32_16x16x32_bf16 v[72:75], v[170:173], v[224:227], v[72:75]
	s_setprio 0
	s_setprio 1
	v_mfma_f32_16x16x32_bf16 v[116:119], v[174:177], v[196:199], v[116:119]
	v_mfma_f32_16x16x32_bf16 v[108:111], v[184:187], v[196:199], v[108:111]
	v_mfma_f32_16x16x32_bf16 v[100:103], v[174:177], v[204:207], v[100:103]
	v_mfma_f32_16x16x32_bf16 v[92:95], v[184:187], v[204:207], v[92:95]
	v_mfma_f32_16x16x32_bf16 v[84:87], v[174:177], v[212:215], v[84:87]
	v_mfma_f32_16x16x32_bf16 v[76:79], v[184:187], v[212:215], v[76:79]
	v_mfma_f32_16x16x32_bf16 v[68:71], v[174:177], v[220:223], v[68:71]
	v_mfma_f32_16x16x32_bf16 v[64:67], v[184:187], v[220:223], v[64:67]
	v_mfma_f32_16x16x32_bf16 v[116:119], v[180:183], v[200:203], v[116:119]
	v_mfma_f32_16x16x32_bf16 v[108:111], v[192:195], v[200:203], v[108:111]
	v_mfma_f32_16x16x32_bf16 v[100:103], v[180:183], v[208:211], v[100:103]
	v_mfma_f32_16x16x32_bf16 v[92:95], v[192:195], v[208:211], v[92:95]
	v_mfma_f32_16x16x32_bf16 v[84:87], v[180:183], v[216:219], v[84:87]
	v_mfma_f32_16x16x32_bf16 v[76:79], v[192:195], v[216:219], v[76:79]
	v_mfma_f32_16x16x32_bf16 v[68:71], v[180:183], v[224:227], v[68:71]
	v_mfma_f32_16x16x32_bf16 v[64:67], v[192:195], v[224:227], v[64:67]
	s_setprio 0
	s_barrier
	s_add_i32 s63, s54, s28
	v_lshl_add_u64 v[166:167], s[24:25], 0, v[132:133]
	s_mov_b32 m0, s63
	ds_read_b128 v[196:199], v154 offset:16384
	ds_read_b128 v[200:203], v154 offset:17408
	ds_read_b128 v[204:207], v154 offset:18432
	ds_read_b128 v[208:211], v154 offset:19456
	ds_read_b128 v[212:215], v154 offset:20480
	ds_read_b128 v[216:219], v154 offset:21504
	ds_read_b128 v[220:223], v154 offset:22528
	ds_read_b128 v[224:227], v154 offset:23552
	global_load_lds_dwordx4 v[166:167], off
	s_add_i32 m0, s63, 0x2000
	s_add_u32 s64, s24, 0x80000
	v_lshl_add_u64 v[188:189], s[24:25], 0, v[128:129]
	s_addc_u32 s65, s25, 0
	s_add_i32 s63, s55, s28
	global_load_lds_dwordx4 v[188:189], off
	v_lshl_add_u64 v[228:229], s[64:65], 0, v[132:133]
	s_mov_b32 m0, s63
	v_lshl_add_u64 v[230:231], s[26:27], 0, v[130:131]
	global_load_lds_dwordx4 v[228:229], off
	v_lshl_add_u64 v[228:229], s[64:65], 0, v[128:129]
	s_add_i32 m0, s63, 0x2000
	s_nop 0
	global_load_lds_dwordx4 v[228:229], off
	s_waitcnt vmcnt(6)
	s_waitcnt lgkmcnt(0)
	s_barrier
; #define PG8_STAGE(bufoff, gbase, voff) do { _Pragma("unroll") for (int _i = 0; _i < 2; ++_i) \
;         __builtin_amdgcn_global_load_lds((const unsigned*)((const char*)(gbase) + (voff)[_i]), (PG8_LAS unsigned*)(lds + (bufoff) + ldsw + _i * 8192), 16, 0, 0); } while (0)
; #define PG8_LDA(dst, b, h) do { _Pragma("unroll") for (int m = 0; m < 4; ++m) _Pragma("unroll") for (int k = 0; k < 2; ++k) dst[m][k] = *(const PG8_LAS bf16x8*)(lds + PG8_SA(b, h) + aoff + m * 2048 + k * 1024); } while (0)
; #define PG8_LDB(dst, b, h) do { _Pragma("unroll") for (int n = 0; n < 2; ++n) _Pragma("unroll") for (int k = 0; k < 2; ++k) dst[n][k] = *(const PG8_LAS bf16x8*)(lds + PG8_SB(b, h) + boff + n * 2048 + k * 1024); } while (0)
; #define PG8_MMA(ai, bj, At, Bt) do { __builtin_amdgcn_s_setprio(1); _Pragma("unroll") for (int m = 0; m < 4; ++m) _Pragma("unroll") for (int n = 0; n < 2; ++n) _Pragma("unroll") for (int k = 0; k < 2; ++k) \
;         acc[ai][bj][m][n] = __builtin_amdgcn_mfma_f32_16x16x32_bf16(Bt[n][k], At[m][k], acc[ai][bj][m][n], 0, 0, 0); __builtin_amdgcn_s_setprio(0); } while (0)
; #define PG8_WAIT_V(n) asm volatile("s_waitcnt vmcnt(" #n ")" ::: "memory")
; #define PG8_WAIT_L(n) asm volatile("s_waitcnt lgkmcnt(" #n ")" ::: "memory")
; #define PG8_BAR __builtin_amdgcn_s_barrier()
; #define PG8_SCHED __builtin_amdgcn_sched_barrier(0)
; template <class Epi, class Sched, bool ALIGN_EPI = false, bool SP2 = false>
; __device__ __forceinline__ void gemm_phase(PG8_LAS unsigned char* lds, const Gemm g, const Sched& S, const Epi& E) {
;     ...
;             PG8_WAIT_V(8); PG8_WAIT_L(0); PG8_BAR; PG8_MMA(1, 0, At, B0); PG8_MMA(1, 1, At, B1); PG8_BAR; PG8_SCHED;
;             PG8_LDB(B0, 1, 0); PG8_LDB(B1, 1, 1); PG8_SCHED; PG8_LDA(At, 1, 0); PG8_STAGE(PG8_SA(0, 1), a2 + hstep, voffA);
;             PG8_WAIT_V(8); PG8_WAIT_L(0); PG8_BAR; PG8_MMA(0, 0, At, B0); PG8_MMA(0, 1, At, B1); PG8_BAR; PG8_SCHED;
	s_setprio 1
	s_waitcnt lgkmcnt(0)
	v_mfma_f32_16x16x32_bf16 v[60:63], v[146:149], v[196:199], v[60:63]
	v_mfma_f32_16x16x32_bf16 v[56:59], v[162:165], v[196:199], v[56:59]
	v_mfma_f32_16x16x32_bf16 v[48:51], v[146:149], v[204:207], v[48:51]
	v_mfma_f32_16x16x32_bf16 v[40:43], v[162:165], v[204:207], v[40:43]
	v_mfma_f32_16x16x32_bf16 v[32:35], v[146:149], v[212:215], v[32:35]
	v_mfma_f32_16x16x32_bf16 v[24:27], v[162:165], v[212:215], v[24:27]
	v_mfma_f32_16x16x32_bf16 v[16:19], v[146:149], v[220:223], v[16:19]
	v_mfma_f32_16x16x32_bf16 v[8:11], v[162:165], v[220:223], v[8:11]
	v_mfma_f32_16x16x32_bf16 v[60:63], v[158:161], v[200:203], v[60:63]
	v_mfma_f32_16x16x32_bf16 v[56:59], v[170:173], v[200:203], v[56:59]
	v_mfma_f32_16x16x32_bf16 v[48:51], v[158:161], v[208:211], v[48:51]
	v_mfma_f32_16x16x32_bf16 v[40:43], v[170:173], v[208:211], v[40:43]
	v_mfma_f32_16x16x32_bf16 v[32:35], v[158:161], v[216:219], v[32:35]
	v_mfma_f32_16x16x32_bf16 v[24:27], v[170:173], v[216:219], v[24:27]
	v_mfma_f32_16x16x32_bf16 v[16:19], v[158:161], v[224:227], v[16:19]
	v_mfma_f32_16x16x32_bf16 v[8:11], v[170:173], v[224:227], v[8:11]
	s_setprio 0
	s_setprio 1
	v_mfma_f32_16x16x32_bf16 v[52:55], v[174:177], v[196:199], v[52:55]
	v_mfma_f32_16x16x32_bf16 v[44:47], v[184:187], v[196:199], v[44:47]
	v_mfma_f32_16x16x32_bf16 v[36:39], v[174:177], v[204:207], v[36:39]
	v_mfma_f32_16x16x32_bf16 v[28:31], v[184:187], v[204:207], v[28:31]
	v_mfma_f32_16x16x32_bf16 v[20:23], v[174:177], v[212:215], v[20:23]
	v_mfma_f32_16x16x32_bf16 v[12:15], v[184:187], v[212:215], v[12:15]
	v_mfma_f32_16x16x32_bf16 v[4:7], v[174:177], v[220:223], v[4:7]
	v_mfma_f32_16x16x32_bf16 v[0:3], v[184:187], v[220:223], v[0:3]
	v_mfma_f32_16x16x32_bf16 v[52:55], v[180:183], v[200:203], v[52:55]
	v_mfma_f32_16x16x32_bf16 v[44:47], v[192:195], v[200:203], v[44:47]
	v_mfma_f32_16x16x32_bf16 v[36:39], v[180:183], v[208:211], v[36:39]
	v_mfma_f32_16x16x32_bf16 v[28:31], v[192:195], v[208:211], v[28:31]
	v_mfma_f32_16x16x32_bf16 v[20:23], v[180:183], v[216:219], v[20:23]
	v_mfma_f32_16x16x32_bf16 v[12:15], v[192:195], v[216:219], v[12:15]
	v_mfma_f32_16x16x32_bf16 v[4:7], v[180:183], v[224:227], v[4:7]
	v_mfma_f32_16x16x32_bf16 v[0:3], v[192:195], v[224:227], v[0:3]
	s_setprio 0
	s_barrier
	s_add_i32 s63, 0, 0x18000
	v_add_u32_e32 v144, s63, v150
	s_add_i32 s64, 0, 0x1c000
	ds_read_b128 v[146:149], v144
	ds_read_b128 v[158:161], v144 offset:1024
	ds_read_b128 v[162:165], v144 offset:2048
	ds_read_b128 v[170:173], v144 offset:3072
	v_add_u32_e32 v144, s64, v150
	ds_read_b128 v[174:177], v144
	ds_read_b128 v[180:183], v144 offset:1024
	ds_read_b128 v[184:187], v144 offset:2048
	ds_read_b128 v[192:195], v144 offset:3072
	v_lshl_add_u64 v[228:229], s[26:27], 0, v[134:135]
	s_mov_b32 m0, s21
	s_nop 0
	global_load_lds_dwordx4 v[228:229], off
	s_mov_b32 m0, s31
	s_nop 0
	global_load_lds_dwordx4 v[230:231], off
	s_add_u32 s26, s26, 0x80000
	s_addc_u32 s27, s27, 0
	s_mov_b32 m0, s33
	v_lshl_add_u64 v[232:233], s[26:27], 0, v[134:135]
	ds_read_b128 v[196:199], v154 offset:32768
	ds_read_b128 v[200:203], v154 offset:33792
	ds_read_b128 v[204:207], v154 offset:34816
	ds_read_b128 v[208:211], v154 offset:35840
	ds_read_b128 v[212:215], v154 offset:36864
	ds_read_b128 v[216:219], v154 offset:37888
	ds_read_b128 v[220:223], v154 offset:38912
	ds_read_b128 v[224:227], v154 offset:39936
	global_load_lds_dwordx4 v[232:233], off
	v_lshl_add_u64 v[232:233], s[26:27], 0, v[130:131]
	s_mov_b32 m0, s34
	s_nop 0
	global_load_lds_dwordx4 v[232:233], off
	s_waitcnt vmcnt(8)
	s_waitcnt lgkmcnt(0)
	s_barrier
	s_setprio 1
	s_waitcnt lgkmcnt(0)
	v_mfma_f32_16x16x32_bf16 v[124:127], v[146:149], v[196:199], v[124:127]
	v_mfma_f32_16x16x32_bf16 v[120:123], v[162:165], v[196:199], v[120:123]
	v_mfma_f32_16x16x32_bf16 v[112:115], v[146:149], v[204:207], v[112:115]
	v_mfma_f32_16x16x32_bf16 v[104:107], v[162:165], v[204:207], v[104:107]
	v_mfma_f32_16x16x32_bf16 v[96:99], v[146:149], v[212:215], v[96:99]
	v_mfma_f32_16x16x32_bf16 v[88:91], v[162:165], v[212:215], v[88:91]
	v_mfma_f32_16x16x32_bf16 v[80:83], v[146:149], v[220:223], v[80:83]
	v_mfma_f32_16x16x32_bf16 v[72:75], v[162:165], v[220:223], v[72:75]
	v_mfma_f32_16x16x32_bf16 v[124:127], v[158:161], v[200:203], v[124:127]
	v_mfma_f32_16x16x32_bf16 v[120:123], v[170:173], v[200:203], v[120:123]
	v_mfma_f32_16x16x32_bf16 v[112:115], v[158:161], v[208:211], v[112:115]
	v_mfma_f32_16x16x32_bf16 v[104:107], v[170:173], v[208:211], v[104:107]
	v_mfma_f32_16x16x32_bf16 v[96:99], v[158:161], v[216:219], v[96:99]
	v_mfma_f32_16x16x32_bf16 v[88:91], v[170:173], v[216:219], v[88:91]
	v_mfma_f32_16x16x32_bf16 v[80:83], v[158:161], v[224:227], v[80:83]
	v_mfma_f32_16x16x32_bf16 v[72:75], v[170:173], v[224:227], v[72:75]
	s_setprio 0
	s_setprio 1
	v_mfma_f32_16x16x32_bf16 v[116:119], v[174:177], v[196:199], v[116:119]
	v_mfma_f32_16x16x32_bf16 v[108:111], v[184:187], v[196:199], v[108:111]
	v_mfma_f32_16x16x32_bf16 v[100:103], v[174:177], v[204:207], v[100:103]
	v_mfma_f32_16x16x32_bf16 v[92:95], v[184:187], v[204:207], v[92:95]
	v_mfma_f32_16x16x32_bf16 v[84:87], v[174:177], v[212:215], v[84:87]
	v_mfma_f32_16x16x32_bf16 v[76:79], v[184:187], v[212:215], v[76:79]
	v_mfma_f32_16x16x32_bf16 v[68:71], v[174:177], v[220:223], v[68:71]
	v_mfma_f32_16x16x32_bf16 v[64:67], v[184:187], v[220:223], v[64:67]
	v_mfma_f32_16x16x32_bf16 v[116:119], v[180:183], v[200:203], v[116:119]
	v_mfma_f32_16x16x32_bf16 v[108:111], v[192:195], v[200:203], v[108:111]
	v_mfma_f32_16x16x32_bf16 v[100:103], v[180:183], v[208:211], v[100:103]
	v_mfma_f32_16x16x32_bf16 v[92:95], v[192:195], v[208:211], v[92:95]
	v_mfma_f32_16x16x32_bf16 v[84:87], v[180:183], v[216:219], v[84:87]
	v_mfma_f32_16x16x32_bf16 v[76:79], v[192:195], v[216:219], v[76:79]
	v_mfma_f32_16x16x32_bf16 v[68:71], v[180:183], v[224:227], v[68:71]
	v_mfma_f32_16x16x32_bf16 v[64:67], v[192:195], v[224:227], v[64:67]
	s_setprio 0
	s_barrier
; #define PG8_STAGE(bufoff, gbase, voff) do { _Pragma("unroll") for (int _i = 0; _i < 2; ++_i) \
;         __builtin_amdgcn_global_load_lds((const unsigned*)((const char*)(gbase) + (voff)[_i]), (PG8_LAS unsigned*)(lds + (bufoff) + ldsw + _i * 8192), 16, 0, 0); } while (0)
; #define PG8_LDA(dst, b, h) do { _Pragma("unroll") for (int m = 0; m < 4; ++m) _Pragma("unroll") for (int k = 0; k < 2; ++k) dst[m][k] = *(const PG8_LAS bf16x8*)(lds + PG8_SA(b, h) + aoff + m * 2048 + k * 1024); } while (0)
; #define PG8_MMA(ai, bj, At, Bt) do { __builtin_amdgcn_s_setprio(1); _Pragma("unroll") for (int m = 0; m < 4; ++m) _Pragma("unroll") for (int n = 0; n < 2; ++n) _Pragma("unroll") for (int k = 0; k < 2; ++k) \
;         acc[ai][bj][m][n] = __builtin_amdgcn_mfma_f32_16x16x32_bf16(Bt[n][k], At[m][k], acc[ai][bj][m][n], 0, 0, 0); __builtin_amdgcn_s_setprio(0); } while (0)
; #define PG8_WAIT_V(n) asm volatile("s_waitcnt vmcnt(" #n ")" ::: "memory")
; #define PG8_WAIT_L(n) asm volatile("s_waitcnt lgkmcnt(" #n ")" ::: "memory")
; #define PG8_BAR __builtin_amdgcn_s_barrier()
; #define PG8_SCHED __builtin_amdgcn_sched_barrier(0)
; template <class Epi, class Sched, bool ALIGN_EPI = false, bool SP2 = false>
; __device__ __forceinline__ void gemm_phase(PG8_LAS unsigned char* lds, const Gemm g, const Sched& S, const Epi& E) {
;     ...
;             PG8_LDA(At, 1, 1); PG8_STAGE(PG8_SB(1, 0), b3, voffB); PG8_STAGE(PG8_SB(1, 1), b3 + hstep, voffB); PG8_STAGE(PG8_SA(1, 0), a3, voffA);
;             PG8_WAIT_V(8); PG8_WAIT_L(0); PG8_BAR; PG8_MMA(1, 0, At, B0); PG8_MMA(1, 1, At, B1); PG8_BAR; PG8_SCHED;
;     ...
;         if constexpr (ALIGN_EPI) { if (wr == 0) PG8_BAR; }
	s_add_i32 s26, s63, s28
	v_lshl_add_u64 v[166:167], v[166:167], 0, s[8:9]
	s_mov_b32 m0, s26
	ds_read_b128 v[196:199], v154 offset:49152
	ds_read_b128 v[200:203], v154 offset:50176
	ds_read_b128 v[204:207], v154 offset:51200
	ds_read_b128 v[208:211], v154 offset:52224
	ds_read_b128 v[212:215], v154 offset:53248
	ds_read_b128 v[216:219], v154 offset:54272
	ds_read_b128 v[220:223], v154 offset:55296
	ds_read_b128 v[224:227], v154 offset:56320
	global_load_lds_dwordx4 v[166:167], off
	s_add_i32 m0, s26, 0x2000
	s_add_u32 s24, s24, 0x80080
	v_lshl_add_u64 v[166:167], v[188:189], 0, s[8:9]
	s_addc_u32 s25, s25, 0
	s_add_i32 s26, s64, s28
	global_load_lds_dwordx4 v[166:167], off
	v_lshl_add_u64 v[166:167], s[24:25], 0, v[132:133]
	s_mov_b32 m0, s26
	s_nop 0
	global_load_lds_dwordx4 v[166:167], off
	v_lshl_add_u64 v[166:167], s[24:25], 0, v[128:129]
	s_add_i32 m0, s26, 0x2000
	s_nop 0
	global_load_lds_dwordx4 v[166:167], off
	v_lshl_add_u64 v[166:167], v[228:229], 0, s[8:9]
	s_mov_b32 m0, s50
	s_nop 0
	global_load_lds_dwordx4 v[166:167], off
	v_lshl_add_u64 v[166:167], v[230:231], 0, s[8:9]
	s_mov_b32 m0, s51
	s_nop 0
	global_load_lds_dwordx4 v[166:167], off
	s_waitcnt vmcnt(8)
	s_waitcnt lgkmcnt(0)
	s_barrier
	s_setprio 1
	s_waitcnt lgkmcnt(0)
	v_mfma_f32_16x16x32_bf16 v[60:63], v[146:149], v[196:199], v[60:63]
	v_mfma_f32_16x16x32_bf16 v[56:59], v[162:165], v[196:199], v[56:59]
	v_mfma_f32_16x16x32_bf16 v[48:51], v[146:149], v[204:207], v[48:51]
	v_mfma_f32_16x16x32_bf16 v[40:43], v[162:165], v[204:207], v[40:43]
	v_mfma_f32_16x16x32_bf16 v[32:35], v[146:149], v[212:215], v[32:35]
	v_mfma_f32_16x16x32_bf16 v[24:27], v[162:165], v[212:215], v[24:27]
	v_mfma_f32_16x16x32_bf16 v[16:19], v[146:149], v[220:223], v[16:19]
	v_mfma_f32_16x16x32_bf16 v[8:11], v[162:165], v[220:223], v[8:11]
	v_mfma_f32_16x16x32_bf16 v[60:63], v[158:161], v[200:203], v[60:63]
	v_mfma_f32_16x16x32_bf16 v[56:59], v[170:173], v[200:203], v[56:59]
	v_mfma_f32_16x16x32_bf16 v[48:51], v[158:161], v[208:211], v[48:51]
	v_mfma_f32_16x16x32_bf16 v[40:43], v[170:173], v[208:211], v[40:43]
	v_mfma_f32_16x16x32_bf16 v[32:35], v[158:161], v[216:219], v[32:35]
	v_mfma_f32_16x16x32_bf16 v[24:27], v[170:173], v[216:219], v[24:27]
	v_mfma_f32_16x16x32_bf16 v[16:19], v[158:161], v[224:227], v[16:19]
	v_mfma_f32_16x16x32_bf16 v[8:11], v[170:173], v[224:227], v[8:11]
	s_setprio 0
	s_setprio 1
	v_mfma_f32_16x16x32_bf16 v[52:55], v[174:177], v[196:199], v[52:55]
	v_mfma_f32_16x16x32_bf16 v[44:47], v[184:187], v[196:199], v[44:47]
	v_mfma_f32_16x16x32_bf16 v[36:39], v[174:177], v[204:207], v[36:39]
	v_mfma_f32_16x16x32_bf16 v[28:31], v[184:187], v[204:207], v[28:31]
	v_mfma_f32_16x16x32_bf16 v[20:23], v[174:177], v[212:215], v[20:23]
	v_mfma_f32_16x16x32_bf16 v[12:15], v[184:187], v[212:215], v[12:15]
	v_mfma_f32_16x16x32_bf16 v[4:7], v[174:177], v[220:223], v[4:7]
	v_mfma_f32_16x16x32_bf16 v[0:3], v[184:187], v[220:223], v[0:3]
	v_mfma_f32_16x16x32_bf16 v[52:55], v[180:183], v[200:203], v[52:55]
	v_mfma_f32_16x16x32_bf16 v[44:47], v[192:195], v[200:203], v[44:47]
	v_mfma_f32_16x16x32_bf16 v[36:39], v[180:183], v[208:211], v[36:39]
	v_mfma_f32_16x16x32_bf16 v[28:31], v[192:195], v[208:211], v[28:31]
	v_mfma_f32_16x16x32_bf16 v[20:23], v[180:183], v[216:219], v[20:23]
	v_mfma_f32_16x16x32_bf16 v[12:15], v[192:195], v[216:219], v[12:15]
	v_mfma_f32_16x16x32_bf16 v[4:7], v[180:183], v[224:227], v[4:7]
	v_mfma_f32_16x16x32_bf16 v[0:3], v[192:195], v[224:227], v[0:3]
	s_setprio 0
	s_barrier
	s_add_i32 s62, s62, 2
	s_add_u32 s22, s22, 0x100
	s_addc_u32 s23, s23, 0
	s_add_u32 s60, s60, 0x100
	s_addc_u32 s61, s61, 0
	s_cmp_gt_u32 s62, 29
	s_cbranch_scc0 .LBB0_134
	s_and_b64 vcc, exec, s[10:11]
	s_cbranch_vccz .LBB0_137
	s_barrier

; #define PG8_STAGE(bufoff, gbase, voff) do { _Pragma("unroll") for (int _i = 0; _i < 2; ++_i) \
;         __builtin_amdgcn_global_load_lds((const unsigned*)((const char*)(gbase) + (voff)[_i]), (PG8_LAS unsigned*)(lds + (bufoff) + ldsw + _i * 8192), 16, 0, 0); } while (0)
; #define PG8_LDA(dst, b, h) do { _Pragma("unroll") for (int m = 0; m < 4; ++m) _Pragma("unroll") for (int k = 0; k < 2; ++k) dst[m][k] = *(const PG8_LAS bf16x8*)(lds + PG8_SA(b, h) + aoff + m * 2048 + k * 1024); } while (0)
; #define PG8_LDB(dst, b, h) do { _Pragma("unroll") for (int n = 0; n < 2; ++n) _Pragma("unroll") for (int k = 0; k < 2; ++k) dst[n][k] = *(const PG8_LAS bf16x8*)(lds + PG8_SB(b, h) + boff + n * 2048 + k * 1024); } while (0)
; #define PG8_MMA(ai, bj, At, Bt) do { __builtin_amdgcn_s_setprio(1); _Pragma("unroll") for (int m = 0; m < 4; ++m) _Pragma("unroll") for (int n = 0; n < 2; ++n) _Pragma("unroll") for (int k = 0; k < 2; ++k) \
;         acc[ai][bj][m][n] = __builtin_amdgcn_mfma_f32_16x16x32_bf16(Bt[n][k], At[m][k], acc[ai][bj][m][n], 0, 0, 0); __builtin_amdgcn_s_setprio(0); } while (0)
; #define PG8_WAIT_V(n) asm volatile("s_waitcnt vmcnt(" #n ")" ::: "memory")
; #define PG8_WAIT_L(n) asm volatile("s_waitcnt lgkmcnt(" #n ")" ::: "memory")
; #define PG8_BAR __builtin_amdgcn_s_barrier()
; #define PG8_SCHED __builtin_amdgcn_sched_barrier(0)
; template <class Epi, class Sched, bool ALIGN_EPI = false, bool SP2 = false>
; __device__ __forceinline__ void gemm_phase(PG8_LAS unsigned char* lds, const Gemm g, const Sched& S, const Epi& E) {
;     ...
;             PG8_LDB(B0, 0, 0); PG8_LDB(B1, 0, 1); PG8_SCHED; PG8_LDA(At, 0, 0); PG8_STAGE(PG8_SA(1, 1), a1 + hstep, voffA);
;             PG8_WAIT_V(8); PG8_WAIT_L(0); PG8_BAR; PG8_MMA(0, 0, At, B0); PG8_MMA(0, 1, At, B1); PG8_BAR; PG8_SCHED;
;             PG8_LDA(At, 0, 1); PG8_STAGE(PG8_SB(0, 0), b2, voffB); PG8_STAGE(PG8_SB(0, 1), b2 + hstep, voffB); PG8_STAGE(PG8_SA(0, 0), a2, voffA);
;             PG8_WAIT_V(8); PG8_WAIT_L(0); PG8_BAR; PG8_MMA(1, 0, At, B0); PG8_MMA(1, 1, At, B1); PG8_BAR; PG8_SCHED;
.LBB0_466:
	ds_read_b128 v[112:115], v216
	ds_read_b128 v[116:119], v216 offset:1024
	ds_read_b128 v[120:123], v216 offset:2048
	ds_read_b128 v[124:127], v216 offset:3072
	ds_read_b128 v[172:175], v217
	ds_read_b128 v[176:179], v217 offset:1024
	ds_read_b128 v[180:183], v217 offset:2048
	ds_read_b128 v[184:187], v217 offset:3072
	s_add_u32 s30, s6, 0xfff80080
	s_addc_u32 s31, s7, -1
	s_cmp_eq_u32 s43, 28
	s_cselect_b32 s35, s33, s31
	s_cselect_b32 s34, s42, s30
	s_cselect_b32 s31, s15, s29
	s_cselect_b32 s30, s14, s28
	v_lshl_add_u64 v[166:167], s[6:7], 0, v[162:163]
	s_add_i32 m0, s13, 0xc000
	ds_read_b128 v[188:191], v218
	ds_read_b128 v[192:195], v218 offset:1024
	ds_read_b128 v[196:199], v218 offset:2048
	ds_read_b128 v[200:203], v218 offset:3072
	ds_read_b128 v[204:207], v218 offset:4096
	ds_read_b128 v[222:225], v218 offset:5120
	ds_read_b128 v[226:229], v218 offset:6144
	ds_read_b128 v[230:233], v218 offset:7168
	global_load_lds_dwordx4 v[166:167], off
	v_lshl_add_u64 v[166:167], s[6:7], 0, v[164:165]
	s_add_i32 m0, s13, 0xe000
	s_nop 0
	global_load_lds_dwordx4 v[166:167], off
	s_waitcnt vmcnt(8)
	s_waitcnt lgkmcnt(0)
	s_barrier
	s_setprio 1
	s_waitcnt lgkmcnt(0)
	v_mfma_f32_16x16x32_bf16 v[140:143], v[112:115], v[188:191], v[140:143]
	v_mfma_f32_16x16x32_bf16 v[136:139], v[120:123], v[188:191], v[136:139]
	v_mfma_f32_16x16x32_bf16 v[108:111], v[112:115], v[196:199], v[108:111]
	v_mfma_f32_16x16x32_bf16 v[104:107], v[120:123], v[196:199], v[104:107]
	v_mfma_f32_16x16x32_bf16 v[92:95], v[112:115], v[204:207], v[92:95]
	v_mfma_f32_16x16x32_bf16 v[88:91], v[120:123], v[204:207], v[88:91]
	v_mfma_f32_16x16x32_bf16 v[76:79], v[112:115], v[226:229], v[76:79]
	v_mfma_f32_16x16x32_bf16 v[72:75], v[120:123], v[226:229], v[72:75]
	v_mfma_f32_16x16x32_bf16 v[140:143], v[116:119], v[192:195], v[140:143]
	v_mfma_f32_16x16x32_bf16 v[136:139], v[124:127], v[192:195], v[136:139]
	v_mfma_f32_16x16x32_bf16 v[108:111], v[116:119], v[200:203], v[108:111]
	v_mfma_f32_16x16x32_bf16 v[104:107], v[124:127], v[200:203], v[104:107]
	v_mfma_f32_16x16x32_bf16 v[92:95], v[116:119], v[222:225], v[92:95]
	v_mfma_f32_16x16x32_bf16 v[88:91], v[124:127], v[222:225], v[88:91]
	v_mfma_f32_16x16x32_bf16 v[76:79], v[116:119], v[230:233], v[76:79]
	v_mfma_f32_16x16x32_bf16 v[72:75], v[124:127], v[230:233], v[72:75]
	s_setprio 0
	s_setprio 1
	v_mfma_f32_16x16x32_bf16 v[132:135], v[172:175], v[188:191], v[132:135]
	v_mfma_f32_16x16x32_bf16 v[128:131], v[180:183], v[188:191], v[128:131]
	v_mfma_f32_16x16x32_bf16 v[100:103], v[172:175], v[196:199], v[100:103]
	v_mfma_f32_16x16x32_bf16 v[96:99], v[180:183], v[196:199], v[96:99]
	v_mfma_f32_16x16x32_bf16 v[84:87], v[172:175], v[204:207], v[84:87]
	v_mfma_f32_16x16x32_bf16 v[80:83], v[180:183], v[204:207], v[80:83]
	v_mfma_f32_16x16x32_bf16 v[68:71], v[172:175], v[226:229], v[68:71]
	v_mfma_f32_16x16x32_bf16 v[64:67], v[180:183], v[226:229], v[64:67]
	v_mfma_f32_16x16x32_bf16 v[132:135], v[176:179], v[192:195], v[132:135]
	v_mfma_f32_16x16x32_bf16 v[128:131], v[184:187], v[192:195], v[128:131]
	v_mfma_f32_16x16x32_bf16 v[100:103], v[176:179], v[200:203], v[100:103]
	v_mfma_f32_16x16x32_bf16 v[96:99], v[184:187], v[200:203], v[96:99]
	v_mfma_f32_16x16x32_bf16 v[84:87], v[176:179], v[222:225], v[84:87]
	v_mfma_f32_16x16x32_bf16 v[80:83], v[184:187], v[222:225], v[80:83]
	v_mfma_f32_16x16x32_bf16 v[68:71], v[176:179], v[230:233], v[68:71]
	v_mfma_f32_16x16x32_bf16 v[64:67], v[184:187], v[230:233], v[64:67]
	s_setprio 0
	s_barrier
	s_add_i32 s50, s44, s52
	v_lshl_add_u64 v[166:167], s[30:31], 0, v[148:149]
	s_mov_b32 m0, s50
	ds_read_b128 v[188:191], v218 offset:16384
	ds_read_b128 v[192:195], v218 offset:17408
	ds_read_b128 v[196:199], v218 offset:18432
	ds_read_b128 v[200:203], v218 offset:19456
	ds_read_b128 v[204:207], v218 offset:20480
	ds_read_b128 v[222:225], v218 offset:21504
	ds_read_b128 v[226:229], v218 offset:22528
	ds_read_b128 v[230:233], v218 offset:23552
	global_load_lds_dwordx4 v[166:167], off
	s_add_i32 m0, s50, 0x2000
	s_add_u32 s50, s30, 0x80000
	v_lshl_add_u64 v[234:235], s[30:31], 0, v[144:145]
	s_addc_u32 s51, s31, 0
	s_add_i32 s80, s45, s52
	global_load_lds_dwordx4 v[234:235], off
	v_lshl_add_u64 v[236:237], s[50:51], 0, v[148:149]
	s_mov_b32 m0, s80
	v_lshl_add_u64 v[238:239], s[34:35], 0, v[146:147]
	global_load_lds_dwordx4 v[236:237], off
	v_lshl_add_u64 v[236:237], s[50:51], 0, v[144:145]
	s_add_i32 m0, s80, 0x2000
	s_nop 0
	global_load_lds_dwordx4 v[236:237], off
	s_waitcnt vmcnt(6)
	s_waitcnt lgkmcnt(0)
	s_barrier
; #define PG8_STAGE(bufoff, gbase, voff) do { _Pragma("unroll") for (int _i = 0; _i < 2; ++_i) \
;         __builtin_amdgcn_global_load_lds((const unsigned*)((const char*)(gbase) + (voff)[_i]), (PG8_LAS unsigned*)(lds + (bufoff) + ldsw + _i * 8192), 16, 0, 0); } while (0)
; #define PG8_LDA(dst, b, h) do { _Pragma("unroll") for (int m = 0; m < 4; ++m) _Pragma("unroll") for (int k = 0; k < 2; ++k) dst[m][k] = *(const PG8_LAS bf16x8*)(lds + PG8_SA(b, h) + aoff + m * 2048 + k * 1024); } while (0)
; #define PG8_LDB(dst, b, h) do { _Pragma("unroll") for (int n = 0; n < 2; ++n) _Pragma("unroll") for (int k = 0; k < 2; ++k) dst[n][k] = *(const PG8_LAS bf16x8*)(lds + PG8_SB(b, h) + boff + n * 2048 + k * 1024); } while (0)
; #define PG8_MMA(ai, bj, At, Bt) do { __builtin_amdgcn_s_setprio(1); _Pragma("unroll") for (int m = 0; m < 4; ++m) _Pragma("unroll") for (int n = 0; n < 2; ++n) _Pragma("unroll") for (int k = 0; k < 2; ++k) \
;         acc[ai][bj][m][n] = __builtin_amdgcn_mfma_f32_16x16x32_bf16(Bt[n][k], At[m][k], acc[ai][bj][m][n], 0, 0, 0); __builtin_amdgcn_s_setprio(0); } while (0)
; #define PG8_WAIT_V(n) asm volatile("s_waitcnt vmcnt(" #n ")" ::: "memory")
; #define PG8_WAIT_L(n) asm volatile("s_waitcnt lgkmcnt(" #n ")" ::: "memory")
; #define PG8_BAR __builtin_amdgcn_s_barrier()
; #define PG8_SCHED __builtin_amdgcn_sched_barrier(0)
; template <class Epi, class Sched, bool ALIGN_EPI = false, bool SP2 = false>
; __device__ __forceinline__ void gemm_phase(PG8_LAS unsigned char* lds, const Gemm g, const Sched& S, const Epi& E) {
;     ...
;             PG8_WAIT_V(8); PG8_WAIT_L(0); PG8_BAR; PG8_MMA(1, 0, At, B0); PG8_MMA(1, 1, At, B1); PG8_BAR; PG8_SCHED;
;             PG8_LDB(B0, 1, 0); PG8_LDB(B1, 1, 1); PG8_SCHED; PG8_LDA(At, 1, 0); PG8_STAGE(PG8_SA(0, 1), a2 + hstep, voffA);
;             PG8_WAIT_V(8); PG8_WAIT_L(0); PG8_BAR; PG8_MMA(0, 0, At, B0); PG8_MMA(0, 1, At, B1); PG8_BAR; PG8_SCHED;
	s_setprio 1
	s_waitcnt lgkmcnt(0)
	v_mfma_f32_16x16x32_bf16 v[60:63], v[112:115], v[188:191], v[60:63]
	v_mfma_f32_16x16x32_bf16 v[56:59], v[120:123], v[188:191], v[56:59]
	v_mfma_f32_16x16x32_bf16 v[44:47], v[112:115], v[196:199], v[44:47]
	v_mfma_f32_16x16x32_bf16 v[40:43], v[120:123], v[196:199], v[40:43]
	v_mfma_f32_16x16x32_bf16 v[28:31], v[112:115], v[204:207], v[28:31]
	v_mfma_f32_16x16x32_bf16 v[24:27], v[120:123], v[204:207], v[24:27]
	v_mfma_f32_16x16x32_bf16 v[12:15], v[112:115], v[226:229], v[12:15]
	v_mfma_f32_16x16x32_bf16 v[8:11], v[120:123], v[226:229], v[8:11]
	v_mfma_f32_16x16x32_bf16 v[60:63], v[116:119], v[192:195], v[60:63]
	v_mfma_f32_16x16x32_bf16 v[56:59], v[124:127], v[192:195], v[56:59]
	v_mfma_f32_16x16x32_bf16 v[44:47], v[116:119], v[200:203], v[44:47]
	v_mfma_f32_16x16x32_bf16 v[40:43], v[124:127], v[200:203], v[40:43]
	v_mfma_f32_16x16x32_bf16 v[28:31], v[116:119], v[222:225], v[28:31]
	v_mfma_f32_16x16x32_bf16 v[24:27], v[124:127], v[222:225], v[24:27]
	v_mfma_f32_16x16x32_bf16 v[12:15], v[116:119], v[230:233], v[12:15]
	v_mfma_f32_16x16x32_bf16 v[8:11], v[124:127], v[230:233], v[8:11]
	s_setprio 0
	s_setprio 1
	v_mfma_f32_16x16x32_bf16 v[52:55], v[172:175], v[188:191], v[52:55]
	v_mfma_f32_16x16x32_bf16 v[48:51], v[180:183], v[188:191], v[48:51]
	v_mfma_f32_16x16x32_bf16 v[36:39], v[172:175], v[196:199], v[36:39]
	v_mfma_f32_16x16x32_bf16 v[32:35], v[180:183], v[196:199], v[32:35]
	v_mfma_f32_16x16x32_bf16 v[20:23], v[172:175], v[204:207], v[20:23]
	v_mfma_f32_16x16x32_bf16 v[16:19], v[180:183], v[204:207], v[16:19]
	v_mfma_f32_16x16x32_bf16 v[4:7], v[172:175], v[226:229], v[4:7]
	v_mfma_f32_16x16x32_bf16 v[0:3], v[180:183], v[226:229], v[0:3]
	v_mfma_f32_16x16x32_bf16 v[52:55], v[176:179], v[192:195], v[52:55]
	v_mfma_f32_16x16x32_bf16 v[48:51], v[184:187], v[192:195], v[48:51]
	v_mfma_f32_16x16x32_bf16 v[36:39], v[176:179], v[200:203], v[36:39]
	v_mfma_f32_16x16x32_bf16 v[32:35], v[184:187], v[200:203], v[32:35]
	v_mfma_f32_16x16x32_bf16 v[20:23], v[176:179], v[222:225], v[20:23]
	v_mfma_f32_16x16x32_bf16 v[16:19], v[184:187], v[222:225], v[16:19]
	v_mfma_f32_16x16x32_bf16 v[4:7], v[176:179], v[230:233], v[4:7]
	v_mfma_f32_16x16x32_bf16 v[0:3], v[184:187], v[230:233], v[0:3]
	s_setprio 0
	s_barrier
	s_add_i32 s50, 0, 0x18000
	s_add_i32 s51, 0, 0x1c000
	v_add_u32_e32 v124, s50, v215
	v_add_u32_e32 v184, s51, v215
	ds_read_b128 v[112:115], v124
	ds_read_b128 v[116:119], v124 offset:1024
	ds_read_b128 v[120:123], v124 offset:2048
	ds_read_b128 v[124:127], v124 offset:3072
	ds_read_b128 v[172:175], v184
	ds_read_b128 v[176:179], v184 offset:1024
	ds_read_b128 v[180:183], v184 offset:2048
	ds_read_b128 v[184:187], v184 offset:3072
	v_lshl_add_u64 v[236:237], s[34:35], 0, v[150:151]
	s_mov_b32 m0, s13
	s_nop 0
	global_load_lds_dwordx4 v[236:237], off
	s_mov_b32 m0, s53
	s_nop 0
	global_load_lds_dwordx4 v[238:239], off
	s_add_u32 s34, s34, 0x80000
	s_addc_u32 s35, s35, 0
	s_mov_b32 m0, s54
	v_lshl_add_u64 v[240:241], s[34:35], 0, v[150:151]
	ds_read_b128 v[188:191], v218 offset:32768
	ds_read_b128 v[192:195], v218 offset:33792
	ds_read_b128 v[196:199], v218 offset:34816
	ds_read_b128 v[200:203], v218 offset:35840
	ds_read_b128 v[204:207], v218 offset:36864
	ds_read_b128 v[222:225], v218 offset:37888
	ds_read_b128 v[226:229], v218 offset:38912
	ds_read_b128 v[230:233], v218 offset:39936
	global_load_lds_dwordx4 v[240:241], off
	v_lshl_add_u64 v[240:241], s[34:35], 0, v[146:147]
	s_mov_b32 m0, s55
	s_nop 0
	global_load_lds_dwordx4 v[240:241], off
	s_waitcnt vmcnt(8)
	s_waitcnt lgkmcnt(0)
	s_barrier
	s_setprio 1
	s_waitcnt lgkmcnt(0)
	v_mfma_f32_16x16x32_bf16 v[140:143], v[112:115], v[188:191], v[140:143]
	v_mfma_f32_16x16x32_bf16 v[136:139], v[120:123], v[188:191], v[136:139]
	v_mfma_f32_16x16x32_bf16 v[108:111], v[112:115], v[196:199], v[108:111]
	v_mfma_f32_16x16x32_bf16 v[104:107], v[120:123], v[196:199], v[104:107]
	v_mfma_f32_16x16x32_bf16 v[92:95], v[112:115], v[204:207], v[92:95]
	v_mfma_f32_16x16x32_bf16 v[88:91], v[120:123], v[204:207], v[88:91]
	v_mfma_f32_16x16x32_bf16 v[76:79], v[112:115], v[226:229], v[76:79]
	v_mfma_f32_16x16x32_bf16 v[72:75], v[120:123], v[226:229], v[72:75]
	v_mfma_f32_16x16x32_bf16 v[140:143], v[116:119], v[192:195], v[140:143]
	v_mfma_f32_16x16x32_bf16 v[136:139], v[124:127], v[192:195], v[136:139]
	v_mfma_f32_16x16x32_bf16 v[108:111], v[116:119], v[200:203], v[108:111]
	v_mfma_f32_16x16x32_bf16 v[104:107], v[124:127], v[200:203], v[104:107]
	v_mfma_f32_16x16x32_bf16 v[92:95], v[116:119], v[222:225], v[92:95]
	v_mfma_f32_16x16x32_bf16 v[88:91], v[124:127], v[222:225], v[88:91]
	v_mfma_f32_16x16x32_bf16 v[76:79], v[116:119], v[230:233], v[76:79]
	v_mfma_f32_16x16x32_bf16 v[72:75], v[124:127], v[230:233], v[72:75]
	s_setprio 0
	s_setprio 1
	v_mfma_f32_16x16x32_bf16 v[132:135], v[172:175], v[188:191], v[132:135]
	v_mfma_f32_16x16x32_bf16 v[128:131], v[180:183], v[188:191], v[128:131]
	v_mfma_f32_16x16x32_bf16 v[100:103], v[172:175], v[196:199], v[100:103]
	v_mfma_f32_16x16x32_bf16 v[96:99], v[180:183], v[196:199], v[96:99]
	v_mfma_f32_16x16x32_bf16 v[84:87], v[172:175], v[204:207], v[84:87]
	v_mfma_f32_16x16x32_bf16 v[80:83], v[180:183], v[204:207], v[80:83]
	v_mfma_f32_16x16x32_bf16 v[68:71], v[172:175], v[226:229], v[68:71]
	v_mfma_f32_16x16x32_bf16 v[64:67], v[180:183], v[226:229], v[64:67]
	v_mfma_f32_16x16x32_bf16 v[132:135], v[176:179], v[192:195], v[132:135]
	v_mfma_f32_16x16x32_bf16 v[128:131], v[184:187], v[192:195], v[128:131]
	v_mfma_f32_16x16x32_bf16 v[100:103], v[176:179], v[200:203], v[100:103]
	v_mfma_f32_16x16x32_bf16 v[96:99], v[184:187], v[200:203], v[96:99]
	v_mfma_f32_16x16x32_bf16 v[84:87], v[176:179], v[222:225], v[84:87]
	v_mfma_f32_16x16x32_bf16 v[80:83], v[184:187], v[222:225], v[80:83]
	v_mfma_f32_16x16x32_bf16 v[68:71], v[176:179], v[230:233], v[68:71]
	v_mfma_f32_16x16x32_bf16 v[64:67], v[184:187], v[230:233], v[64:67]
	s_setprio 0
	s_barrier
; #define PG8_STAGE(bufoff, gbase, voff) do { _Pragma("unroll") for (int _i = 0; _i < 2; ++_i) \
;         __builtin_amdgcn_global_load_lds((const unsigned*)((const char*)(gbase) + (voff)[_i]), (PG8_LAS unsigned*)(lds + (bufoff) + ldsw + _i * 8192), 16, 0, 0); } while (0)
; #define PG8_LDA(dst, b, h) do { _Pragma("unroll") for (int m = 0; m < 4; ++m) _Pragma("unroll") for (int k = 0; k < 2; ++k) dst[m][k] = *(const PG8_LAS bf16x8*)(lds + PG8_SA(b, h) + aoff + m * 2048 + k * 1024); } while (0)
; #define PG8_MMA(ai, bj, At, Bt) do { __builtin_amdgcn_s_setprio(1); _Pragma("unroll") for (int m = 0; m < 4; ++m) _Pragma("unroll") for (int n = 0; n < 2; ++n) _Pragma("unroll") for (int k = 0; k < 2; ++k) \
;         acc[ai][bj][m][n] = __builtin_amdgcn_mfma_f32_16x16x32_bf16(Bt[n][k], At[m][k], acc[ai][bj][m][n], 0, 0, 0); __builtin_amdgcn_s_setprio(0); } while (0)
; #define PG8_WAIT_V(n) asm volatile("s_waitcnt vmcnt(" #n ")" ::: "memory")
; #define PG8_WAIT_L(n) asm volatile("s_waitcnt lgkmcnt(" #n ")" ::: "memory")
; #define PG8_BAR __builtin_amdgcn_s_barrier()
; #define PG8_SCHED __builtin_amdgcn_sched_barrier(0)
; template <class Epi, class Sched, bool ALIGN_EPI = false, bool SP2 = false>
; __device__ __forceinline__ void gemm_phase(PG8_LAS unsigned char* lds, const Gemm g, const Sched& S, const Epi& E) {
;     ...
;             PG8_LDA(At, 1, 1); PG8_STAGE(PG8_SB(1, 0), b3, voffB); PG8_STAGE(PG8_SB(1, 1), b3 + hstep, voffB); PG8_STAGE(PG8_SA(1, 0), a3, voffA);
;             PG8_WAIT_V(8); PG8_WAIT_L(0); PG8_BAR; PG8_MMA(1, 0, At, B0); PG8_MMA(1, 1, At, B1); PG8_BAR; PG8_SCHED;
;     ...
;         if constexpr (ALIGN_EPI) { if (wr == 0) PG8_BAR; }
	s_add_i32 s34, s50, s52
	v_lshl_add_u64 v[166:167], v[166:167], 0, s[22:23]
	s_mov_b32 m0, s34
	ds_read_b128 v[188:191], v218 offset:49152
	ds_read_b128 v[192:195], v218 offset:50176
	ds_read_b128 v[196:199], v218 offset:51200
	ds_read_b128 v[200:203], v218 offset:52224
	ds_read_b128 v[204:207], v218 offset:53248
	ds_read_b128 v[222:225], v218 offset:54272
	ds_read_b128 v[226:229], v218 offset:55296
	ds_read_b128 v[230:233], v218 offset:56320
	global_load_lds_dwordx4 v[166:167], off
	s_add_i32 m0, s34, 0x2000
	s_add_u32 s30, s30, 0x80080
	v_lshl_add_u64 v[166:167], v[234:235], 0, s[22:23]
	s_addc_u32 s31, s31, 0
	s_add_i32 s34, s51, s52
	global_load_lds_dwordx4 v[166:167], off
	v_lshl_add_u64 v[166:167], s[30:31], 0, v[148:149]
	s_mov_b32 m0, s34
	s_nop 0
	global_load_lds_dwordx4 v[166:167], off
	v_lshl_add_u64 v[166:167], s[30:31], 0, v[144:145]
	s_add_i32 m0, s34, 0x2000
	s_nop 0
	global_load_lds_dwordx4 v[166:167], off
	v_lshl_add_u64 v[166:167], v[236:237], 0, s[22:23]
	s_mov_b32 m0, s61
	s_nop 0
	global_load_lds_dwordx4 v[166:167], off
	v_lshl_add_u64 v[166:167], v[238:239], 0, s[22:23]
	s_mov_b32 m0, s62
	s_nop 0
	global_load_lds_dwordx4 v[166:167], off
	s_waitcnt vmcnt(8)
	s_waitcnt lgkmcnt(0)
	s_barrier
	s_setprio 1
	s_waitcnt lgkmcnt(0)
	v_mfma_f32_16x16x32_bf16 v[60:63], v[112:115], v[188:191], v[60:63]
	v_mfma_f32_16x16x32_bf16 v[56:59], v[120:123], v[188:191], v[56:59]
	v_mfma_f32_16x16x32_bf16 v[44:47], v[112:115], v[196:199], v[44:47]
	v_mfma_f32_16x16x32_bf16 v[40:43], v[120:123], v[196:199], v[40:43]
	v_mfma_f32_16x16x32_bf16 v[28:31], v[112:115], v[204:207], v[28:31]
	v_mfma_f32_16x16x32_bf16 v[24:27], v[120:123], v[204:207], v[24:27]
	v_mfma_f32_16x16x32_bf16 v[12:15], v[112:115], v[226:229], v[12:15]
	v_mfma_f32_16x16x32_bf16 v[8:11], v[120:123], v[226:229], v[8:11]
	v_mfma_f32_16x16x32_bf16 v[60:63], v[116:119], v[192:195], v[60:63]
	v_mfma_f32_16x16x32_bf16 v[56:59], v[124:127], v[192:195], v[56:59]
	v_mfma_f32_16x16x32_bf16 v[44:47], v[116:119], v[200:203], v[44:47]
	v_mfma_f32_16x16x32_bf16 v[40:43], v[124:127], v[200:203], v[40:43]
	v_mfma_f32_16x16x32_bf16 v[28:31], v[116:119], v[222:225], v[28:31]
	v_mfma_f32_16x16x32_bf16 v[24:27], v[124:127], v[222:225], v[24:27]
	v_mfma_f32_16x16x32_bf16 v[12:15], v[116:119], v[230:233], v[12:15]
	v_mfma_f32_16x16x32_bf16 v[8:11], v[124:127], v[230:233], v[8:11]
	s_setprio 0
	s_setprio 1
	v_mfma_f32_16x16x32_bf16 v[52:55], v[172:175], v[188:191], v[52:55]
	v_mfma_f32_16x16x32_bf16 v[48:51], v[180:183], v[188:191], v[48:51]
	v_mfma_f32_16x16x32_bf16 v[36:39], v[172:175], v[196:199], v[36:39]
	v_mfma_f32_16x16x32_bf16 v[32:35], v[180:183], v[196:199], v[32:35]
	v_mfma_f32_16x16x32_bf16 v[20:23], v[172:175], v[204:207], v[20:23]
	v_mfma_f32_16x16x32_bf16 v[16:19], v[180:183], v[204:207], v[16:19]
	v_mfma_f32_16x16x32_bf16 v[4:7], v[172:175], v[226:229], v[4:7]
	v_mfma_f32_16x16x32_bf16 v[0:3], v[180:183], v[226:229], v[0:3]
	v_mfma_f32_16x16x32_bf16 v[52:55], v[176:179], v[192:195], v[52:55]
	v_mfma_f32_16x16x32_bf16 v[48:51], v[184:187], v[192:195], v[48:51]
	v_mfma_f32_16x16x32_bf16 v[36:39], v[176:179], v[200:203], v[36:39]
	v_mfma_f32_16x16x32_bf16 v[32:35], v[184:187], v[200:203], v[32:35]
	v_mfma_f32_16x16x32_bf16 v[20:23], v[176:179], v[222:225], v[20:23]
	v_mfma_f32_16x16x32_bf16 v[16:19], v[184:187], v[222:225], v[16:19]
	v_mfma_f32_16x16x32_bf16 v[4:7], v[176:179], v[230:233], v[4:7]
	v_mfma_f32_16x16x32_bf16 v[0:3], v[184:187], v[230:233], v[0:3]
	s_setprio 0
	s_barrier
	s_add_i32 s43, s43, 2
	s_add_u32 s6, s6, 0x100
	s_addc_u32 s7, s7, 0
	s_add_u32 s28, s28, 0x100
	s_addc_u32 s29, s29, 0
	s_cmp_gt_u32 s43, 29
	s_cbranch_scc0 .LBB0_466
	s_and_b64 vcc, exec, s[24:25]
	s_cbranch_vccz .LBB0_469
	s_barrier

; #define PG8_STAGE(bufoff, gbase, voff) do { _Pragma("unroll") for (int _i = 0; _i < 2; ++_i) \
;         __builtin_amdgcn_global_load_lds((const unsigned*)((const char*)(gbase) + (voff)[_i]), (PG8_LAS unsigned*)(lds + (bufoff) + ldsw + _i * 8192), 16, 0, 0); } while (0)
; #define PG8_LDA(dst, b, h) do { _Pragma("unroll") for (int m = 0; m < 4; ++m) _Pragma("unroll") for (int k = 0; k < 2; ++k) dst[m][k] = *(const PG8_LAS bf16x8*)(lds + PG8_SA(b, h) + aoff + m * 2048 + k * 1024); } while (0)
; #define PG8_LDB(dst, b, h) do { _Pragma("unroll") for (int n = 0; n < 2; ++n) _Pragma("unroll") for (int k = 0; k < 2; ++k) dst[n][k] = *(const PG8_LAS bf16x8*)(lds + PG8_SB(b, h) + boff + n * 2048 + k * 1024); } while (0)
; #define PG8_MMA(ai, bj, At, Bt) do { __builtin_amdgcn_s_setprio(1); _Pragma("unroll") for (int m = 0; m < 4; ++m) _Pragma("unroll") for (int n = 0; n < 2; ++n) _Pragma("unroll") for (int k = 0; k < 2; ++k) \
;         acc[ai][bj][m][n] = __builtin_amdgcn_mfma_f32_16x16x32_bf16(Bt[n][k], At[m][k], acc[ai][bj][m][n], 0, 0, 0); __builtin_amdgcn_s_setprio(0); } while (0)
; #define PG8_WAIT_V(n) asm volatile("s_waitcnt vmcnt(" #n ")" ::: "memory")
; #define PG8_WAIT_L(n) asm volatile("s_waitcnt lgkmcnt(" #n ")" ::: "memory")
; #define PG8_BAR __builtin_amdgcn_s_barrier()
; #define PG8_SCHED __builtin_amdgcn_sched_barrier(0)
; template <class Epi, class Sched, bool ALIGN_EPI = false, bool SP2 = false>
; __device__ __forceinline__ void gemm_phase(PG8_LAS unsigned char* lds, const Gemm g, const Sched& S, const Epi& E) {
;     ...
;             PG8_LDB(B0, 0, 0); PG8_LDB(B1, 0, 1); PG8_SCHED; PG8_LDA(At, 0, 0); PG8_STAGE(PG8_SA(1, 1), a1 + hstep, voffA);
;             PG8_WAIT_V(8); PG8_WAIT_L(0); PG8_BAR; PG8_MMA(0, 0, At, B0); PG8_MMA(0, 1, At, B1); PG8_BAR; PG8_SCHED;
;             PG8_LDA(At, 0, 1); PG8_STAGE(PG8_SB(0, 0), b2, voffB); PG8_STAGE(PG8_SB(0, 1), b2 + hstep, voffB); PG8_STAGE(PG8_SA(0, 0), a2, voffA);
;             PG8_WAIT_V(8); PG8_WAIT_L(0); PG8_BAR; PG8_MMA(1, 0, At, B0); PG8_MMA(1, 1, At, B1); PG8_BAR; PG8_SCHED;
.LBB0_593:
	ds_read_b128 v[144:147], v151
	ds_read_b128 v[154:157], v151 offset:1024
	ds_read_b128 v[158:161], v151 offset:2048
	ds_read_b128 v[162:165], v151 offset:3072
	ds_read_b128 v[172:175], v152
	ds_read_b128 v[176:179], v152 offset:1024
	ds_read_b128 v[180:183], v152 offset:2048
	ds_read_b128 v[184:187], v152 offset:3072
	s_add_u32 s26, s24, 0xfff80080
	s_addc_u32 s27, s25, -1
	s_cmp_eq_u32 s55, 28
	s_cselect_b32 s29, s17, s27
	s_cselect_b32 s28, s51, s26
	s_cselect_b32 s27, s15, s54
	s_cselect_b32 s26, s52, s53
	v_lshl_add_u64 v[166:167], s[24:25], 0, v[136:137]
	s_add_i32 m0, s23, 0xc000
	ds_read_b128 v[188:191], v153
	ds_read_b128 v[192:195], v153 offset:1024
	ds_read_b128 v[196:199], v153 offset:2048
	ds_read_b128 v[200:203], v153 offset:3072
	ds_read_b128 v[204:207], v153 offset:4096
	ds_read_b128 v[214:217], v153 offset:5120
	ds_read_b128 v[218:221], v153 offset:6144
	ds_read_b128 v[222:225], v153 offset:7168
	global_load_lds_dwordx4 v[166:167], off
	v_lshl_add_u64 v[166:167], s[24:25], 0, v[138:139]
	s_add_i32 m0, s23, 0xe000
	s_nop 0
	global_load_lds_dwordx4 v[166:167], off
	s_waitcnt vmcnt(8)
	s_waitcnt lgkmcnt(0)
	s_barrier
	s_setprio 1
	s_waitcnt lgkmcnt(0)
	v_mfma_f32_16x16x32_bf16 v[124:127], v[144:147], v[188:191], v[124:127]
	v_mfma_f32_16x16x32_bf16 v[116:119], v[158:161], v[188:191], v[116:119]
	v_mfma_f32_16x16x32_bf16 v[108:111], v[144:147], v[196:199], v[108:111]
	v_mfma_f32_16x16x32_bf16 v[100:103], v[158:161], v[196:199], v[100:103]
	v_mfma_f32_16x16x32_bf16 v[92:95], v[144:147], v[204:207], v[92:95]
	v_mfma_f32_16x16x32_bf16 v[84:87], v[158:161], v[204:207], v[84:87]
	v_mfma_f32_16x16x32_bf16 v[76:79], v[144:147], v[218:221], v[76:79]
	v_mfma_f32_16x16x32_bf16 v[68:71], v[158:161], v[218:221], v[68:71]
	v_mfma_f32_16x16x32_bf16 v[124:127], v[154:157], v[192:195], v[124:127]
	v_mfma_f32_16x16x32_bf16 v[116:119], v[162:165], v[192:195], v[116:119]
	v_mfma_f32_16x16x32_bf16 v[108:111], v[154:157], v[200:203], v[108:111]
	v_mfma_f32_16x16x32_bf16 v[100:103], v[162:165], v[200:203], v[100:103]
	v_mfma_f32_16x16x32_bf16 v[92:95], v[154:157], v[214:217], v[92:95]
	v_mfma_f32_16x16x32_bf16 v[84:87], v[162:165], v[214:217], v[84:87]
	v_mfma_f32_16x16x32_bf16 v[76:79], v[154:157], v[222:225], v[76:79]
	v_mfma_f32_16x16x32_bf16 v[68:71], v[162:165], v[222:225], v[68:71]
	s_setprio 0
	s_setprio 1
	v_mfma_f32_16x16x32_bf16 v[120:123], v[172:175], v[188:191], v[120:123]
	v_mfma_f32_16x16x32_bf16 v[112:115], v[180:183], v[188:191], v[112:115]
	v_mfma_f32_16x16x32_bf16 v[104:107], v[172:175], v[196:199], v[104:107]
	v_mfma_f32_16x16x32_bf16 v[96:99], v[180:183], v[196:199], v[96:99]
	v_mfma_f32_16x16x32_bf16 v[88:91], v[172:175], v[204:207], v[88:91]
	v_mfma_f32_16x16x32_bf16 v[80:83], v[180:183], v[204:207], v[80:83]
	v_mfma_f32_16x16x32_bf16 v[72:75], v[172:175], v[218:221], v[72:75]
	v_mfma_f32_16x16x32_bf16 v[64:67], v[180:183], v[218:221], v[64:67]
	v_mfma_f32_16x16x32_bf16 v[120:123], v[176:179], v[192:195], v[120:123]
	v_mfma_f32_16x16x32_bf16 v[112:115], v[184:187], v[192:195], v[112:115]
	v_mfma_f32_16x16x32_bf16 v[104:107], v[176:179], v[200:203], v[104:107]
	v_mfma_f32_16x16x32_bf16 v[96:99], v[184:187], v[200:203], v[96:99]
	v_mfma_f32_16x16x32_bf16 v[88:91], v[176:179], v[214:217], v[88:91]
	v_mfma_f32_16x16x32_bf16 v[80:83], v[184:187], v[214:217], v[80:83]
	v_mfma_f32_16x16x32_bf16 v[72:75], v[176:179], v[222:225], v[72:75]
	v_mfma_f32_16x16x32_bf16 v[64:67], v[184:187], v[222:225], v[64:67]
	s_setprio 0
	s_barrier
	s_add_i32 s56, s43, s2
	v_lshl_add_u64 v[166:167], s[26:27], 0, v[132:133]
	s_mov_b32 m0, s56
	ds_read_b128 v[188:191], v153 offset:16384
	ds_read_b128 v[192:195], v153 offset:17408
	ds_read_b128 v[196:199], v153 offset:18432
	ds_read_b128 v[200:203], v153 offset:19456
	ds_read_b128 v[204:207], v153 offset:20480
	ds_read_b128 v[214:217], v153 offset:21504
	ds_read_b128 v[218:221], v153 offset:22528
	ds_read_b128 v[222:225], v153 offset:23552
	global_load_lds_dwordx4 v[166:167], off
	s_add_i32 m0, s56, 0x2000
	s_add_u32 s56, s26, 0x80000
	v_lshl_add_u64 v[226:227], s[26:27], 0, v[128:129]
	s_addc_u32 s57, s27, 0
	s_add_i32 s58, s44, s2
	global_load_lds_dwordx4 v[226:227], off
	v_lshl_add_u64 v[228:229], s[56:57], 0, v[132:133]
	s_mov_b32 m0, s58
	v_lshl_add_u64 v[230:231], s[28:29], 0, v[130:131]
	global_load_lds_dwordx4 v[228:229], off
	v_lshl_add_u64 v[228:229], s[56:57], 0, v[128:129]
	s_add_i32 m0, s58, 0x2000
	s_nop 0
	global_load_lds_dwordx4 v[228:229], off
	s_waitcnt vmcnt(6)
	s_waitcnt lgkmcnt(0)
	s_barrier
; #define PG8_STAGE(bufoff, gbase, voff) do { _Pragma("unroll") for (int _i = 0; _i < 2; ++_i) \
;         __builtin_amdgcn_global_load_lds((const unsigned*)((const char*)(gbase) + (voff)[_i]), (PG8_LAS unsigned*)(lds + (bufoff) + ldsw + _i * 8192), 16, 0, 0); } while (0)
; #define PG8_LDA(dst, b, h) do { _Pragma("unroll") for (int m = 0; m < 4; ++m) _Pragma("unroll") for (int k = 0; k < 2; ++k) dst[m][k] = *(const PG8_LAS bf16x8*)(lds + PG8_SA(b, h) + aoff + m * 2048 + k * 1024); } while (0)
; #define PG8_LDB(dst, b, h) do { _Pragma("unroll") for (int n = 0; n < 2; ++n) _Pragma("unroll") for (int k = 0; k < 2; ++k) dst[n][k] = *(const PG8_LAS bf16x8*)(lds + PG8_SB(b, h) + boff + n * 2048 + k * 1024); } while (0)
; #define PG8_MMA(ai, bj, At, Bt) do { __builtin_amdgcn_s_setprio(1); _Pragma("unroll") for (int m = 0; m < 4; ++m) _Pragma("unroll") for (int n = 0; n < 2; ++n) _Pragma("unroll") for (int k = 0; k < 2; ++k) \
;         acc[ai][bj][m][n] = __builtin_amdgcn_mfma_f32_16x16x32_bf16(Bt[n][k], At[m][k], acc[ai][bj][m][n], 0, 0, 0); __builtin_amdgcn_s_setprio(0); } while (0)
; #define PG8_WAIT_V(n) asm volatile("s_waitcnt vmcnt(" #n ")" ::: "memory")
; #define PG8_WAIT_L(n) asm volatile("s_waitcnt lgkmcnt(" #n ")" ::: "memory")
; #define PG8_BAR __builtin_amdgcn_s_barrier()
; #define PG8_SCHED __builtin_amdgcn_sched_barrier(0)
; template <class Epi, class Sched, bool ALIGN_EPI = false, bool SP2 = false>
; __device__ __forceinline__ void gemm_phase(PG8_LAS unsigned char* lds, const Gemm g, const Sched& S, const Epi& E) {
;     ...
;             PG8_WAIT_V(8); PG8_WAIT_L(0); PG8_BAR; PG8_MMA(1, 0, At, B0); PG8_MMA(1, 1, At, B1); PG8_BAR; PG8_SCHED;
;             PG8_LDB(B0, 1, 0); PG8_LDB(B1, 1, 1); PG8_SCHED; PG8_LDA(At, 1, 0); PG8_STAGE(PG8_SA(0, 1), a2 + hstep, voffA);
;             PG8_WAIT_V(8); PG8_WAIT_L(0); PG8_BAR; PG8_MMA(0, 0, At, B0); PG8_MMA(0, 1, At, B1); PG8_BAR; PG8_SCHED;
	s_setprio 1
	s_waitcnt lgkmcnt(0)
	v_mfma_f32_16x16x32_bf16 v[60:63], v[144:147], v[188:191], v[60:63]
	v_mfma_f32_16x16x32_bf16 v[52:55], v[158:161], v[188:191], v[52:55]
	v_mfma_f32_16x16x32_bf16 v[44:47], v[144:147], v[196:199], v[44:47]
	v_mfma_f32_16x16x32_bf16 v[36:39], v[158:161], v[196:199], v[36:39]
	v_mfma_f32_16x16x32_bf16 v[28:31], v[144:147], v[204:207], v[28:31]
	v_mfma_f32_16x16x32_bf16 v[20:23], v[158:161], v[204:207], v[20:23]
	v_mfma_f32_16x16x32_bf16 v[12:15], v[144:147], v[218:221], v[12:15]
	v_mfma_f32_16x16x32_bf16 v[4:7], v[158:161], v[218:221], v[4:7]
	v_mfma_f32_16x16x32_bf16 v[60:63], v[154:157], v[192:195], v[60:63]
	v_mfma_f32_16x16x32_bf16 v[52:55], v[162:165], v[192:195], v[52:55]
	v_mfma_f32_16x16x32_bf16 v[44:47], v[154:157], v[200:203], v[44:47]
	v_mfma_f32_16x16x32_bf16 v[36:39], v[162:165], v[200:203], v[36:39]
	v_mfma_f32_16x16x32_bf16 v[28:31], v[154:157], v[214:217], v[28:31]
	v_mfma_f32_16x16x32_bf16 v[20:23], v[162:165], v[214:217], v[20:23]
	v_mfma_f32_16x16x32_bf16 v[12:15], v[154:157], v[222:225], v[12:15]
	v_mfma_f32_16x16x32_bf16 v[4:7], v[162:165], v[222:225], v[4:7]
	s_setprio 0
	s_setprio 1
	v_mfma_f32_16x16x32_bf16 v[56:59], v[172:175], v[188:191], v[56:59]
	v_mfma_f32_16x16x32_bf16 v[48:51], v[180:183], v[188:191], v[48:51]
	v_mfma_f32_16x16x32_bf16 v[40:43], v[172:175], v[196:199], v[40:43]
	v_mfma_f32_16x16x32_bf16 v[32:35], v[180:183], v[196:199], v[32:35]
	v_mfma_f32_16x16x32_bf16 v[24:27], v[172:175], v[204:207], v[24:27]
	v_mfma_f32_16x16x32_bf16 v[16:19], v[180:183], v[204:207], v[16:19]
	v_mfma_f32_16x16x32_bf16 v[8:11], v[172:175], v[218:221], v[8:11]
	v_mfma_f32_16x16x32_bf16 v[0:3], v[180:183], v[218:221], v[0:3]
	v_mfma_f32_16x16x32_bf16 v[56:59], v[176:179], v[192:195], v[56:59]
	v_mfma_f32_16x16x32_bf16 v[48:51], v[184:187], v[192:195], v[48:51]
	v_mfma_f32_16x16x32_bf16 v[40:43], v[176:179], v[200:203], v[40:43]
	v_mfma_f32_16x16x32_bf16 v[32:35], v[184:187], v[200:203], v[32:35]
	v_mfma_f32_16x16x32_bf16 v[24:27], v[176:179], v[214:217], v[24:27]
	v_mfma_f32_16x16x32_bf16 v[16:19], v[184:187], v[214:217], v[16:19]
	v_mfma_f32_16x16x32_bf16 v[8:11], v[176:179], v[222:225], v[8:11]
	v_mfma_f32_16x16x32_bf16 v[0:3], v[184:187], v[222:225], v[0:3]
	s_setprio 0
	s_barrier
	s_add_i32 s56, 0, 0x18000
	s_add_i32 s57, 0, 0x1c000
	v_add_u32_e32 v162, s56, v149
	v_add_u32_e32 v184, s57, v149
	ds_read_b128 v[144:147], v162
	ds_read_b128 v[154:157], v162 offset:1024
	ds_read_b128 v[158:161], v162 offset:2048
	ds_read_b128 v[162:165], v162 offset:3072
	ds_read_b128 v[172:175], v184
	ds_read_b128 v[176:179], v184 offset:1024
	ds_read_b128 v[180:183], v184 offset:2048
	ds_read_b128 v[184:187], v184 offset:3072
	v_lshl_add_u64 v[228:229], s[28:29], 0, v[134:135]
	s_mov_b32 m0, s23
	s_nop 0
	global_load_lds_dwordx4 v[228:229], off
	s_mov_b32 m0, s33
	s_nop 0
	global_load_lds_dwordx4 v[230:231], off
	s_add_u32 s28, s28, 0x80000
	s_addc_u32 s29, s29, 0
	s_mov_b32 m0, s34
	v_lshl_add_u64 v[232:233], s[28:29], 0, v[134:135]
	ds_read_b128 v[188:191], v153 offset:32768
	ds_read_b128 v[192:195], v153 offset:33792
	ds_read_b128 v[196:199], v153 offset:34816
	ds_read_b128 v[200:203], v153 offset:35840
	ds_read_b128 v[204:207], v153 offset:36864
	ds_read_b128 v[214:217], v153 offset:37888
	ds_read_b128 v[218:221], v153 offset:38912
	ds_read_b128 v[222:225], v153 offset:39936
	global_load_lds_dwordx4 v[232:233], off
	v_lshl_add_u64 v[232:233], s[28:29], 0, v[130:131]
	s_mov_b32 m0, s35
	s_nop 0
	global_load_lds_dwordx4 v[232:233], off
	s_waitcnt vmcnt(8)
	s_waitcnt lgkmcnt(0)
	s_barrier
	s_setprio 1
	s_waitcnt lgkmcnt(0)
	v_mfma_f32_16x16x32_bf16 v[124:127], v[144:147], v[188:191], v[124:127]
	v_mfma_f32_16x16x32_bf16 v[116:119], v[158:161], v[188:191], v[116:119]
	v_mfma_f32_16x16x32_bf16 v[108:111], v[144:147], v[196:199], v[108:111]
	v_mfma_f32_16x16x32_bf16 v[100:103], v[158:161], v[196:199], v[100:103]
	v_mfma_f32_16x16x32_bf16 v[92:95], v[144:147], v[204:207], v[92:95]
	v_mfma_f32_16x16x32_bf16 v[84:87], v[158:161], v[204:207], v[84:87]
	v_mfma_f32_16x16x32_bf16 v[76:79], v[144:147], v[218:221], v[76:79]
	v_mfma_f32_16x16x32_bf16 v[68:71], v[158:161], v[218:221], v[68:71]
	v_mfma_f32_16x16x32_bf16 v[124:127], v[154:157], v[192:195], v[124:127]
	v_mfma_f32_16x16x32_bf16 v[116:119], v[162:165], v[192:195], v[116:119]
	v_mfma_f32_16x16x32_bf16 v[108:111], v[154:157], v[200:203], v[108:111]
	v_mfma_f32_16x16x32_bf16 v[100:103], v[162:165], v[200:203], v[100:103]
	v_mfma_f32_16x16x32_bf16 v[92:95], v[154:157], v[214:217], v[92:95]
	v_mfma_f32_16x16x32_bf16 v[84:87], v[162:165], v[214:217], v[84:87]
	v_mfma_f32_16x16x32_bf16 v[76:79], v[154:157], v[222:225], v[76:79]
	v_mfma_f32_16x16x32_bf16 v[68:71], v[162:165], v[222:225], v[68:71]
	s_setprio 0
	s_setprio 1
	v_mfma_f32_16x16x32_bf16 v[120:123], v[172:175], v[188:191], v[120:123]
	v_mfma_f32_16x16x32_bf16 v[112:115], v[180:183], v[188:191], v[112:115]
	v_mfma_f32_16x16x32_bf16 v[104:107], v[172:175], v[196:199], v[104:107]
	v_mfma_f32_16x16x32_bf16 v[96:99], v[180:183], v[196:199], v[96:99]
	v_mfma_f32_16x16x32_bf16 v[88:91], v[172:175], v[204:207], v[88:91]
	v_mfma_f32_16x16x32_bf16 v[80:83], v[180:183], v[204:207], v[80:83]
	v_mfma_f32_16x16x32_bf16 v[72:75], v[172:175], v[218:221], v[72:75]
	v_mfma_f32_16x16x32_bf16 v[64:67], v[180:183], v[218:221], v[64:67]
	v_mfma_f32_16x16x32_bf16 v[120:123], v[176:179], v[192:195], v[120:123]
	v_mfma_f32_16x16x32_bf16 v[112:115], v[184:187], v[192:195], v[112:115]
	v_mfma_f32_16x16x32_bf16 v[104:107], v[176:179], v[200:203], v[104:107]
	v_mfma_f32_16x16x32_bf16 v[96:99], v[184:187], v[200:203], v[96:99]
	v_mfma_f32_16x16x32_bf16 v[88:91], v[176:179], v[214:217], v[88:91]
	v_mfma_f32_16x16x32_bf16 v[80:83], v[184:187], v[214:217], v[80:83]
	v_mfma_f32_16x16x32_bf16 v[72:75], v[176:179], v[222:225], v[72:75]
	v_mfma_f32_16x16x32_bf16 v[64:67], v[184:187], v[222:225], v[64:67]
	s_setprio 0
	s_barrier
; #define PG8_STAGE(bufoff, gbase, voff) do { _Pragma("unroll") for (int _i = 0; _i < 2; ++_i) \
;         __builtin_amdgcn_global_load_lds((const unsigned*)((const char*)(gbase) + (voff)[_i]), (PG8_LAS unsigned*)(lds + (bufoff) + ldsw + _i * 8192), 16, 0, 0); } while (0)
; #define PG8_LDA(dst, b, h) do { _Pragma("unroll") for (int m = 0; m < 4; ++m) _Pragma("unroll") for (int k = 0; k < 2; ++k) dst[m][k] = *(const PG8_LAS bf16x8*)(lds + PG8_SA(b, h) + aoff + m * 2048 + k * 1024); } while (0)
; #define PG8_MMA(ai, bj, At, Bt) do { __builtin_amdgcn_s_setprio(1); _Pragma("unroll") for (int m = 0; m < 4; ++m) _Pragma("unroll") for (int n = 0; n < 2; ++n) _Pragma("unroll") for (int k = 0; k < 2; ++k) \
;         acc[ai][bj][m][n] = __builtin_amdgcn_mfma_f32_16x16x32_bf16(Bt[n][k], At[m][k], acc[ai][bj][m][n], 0, 0, 0); __builtin_amdgcn_s_setprio(0); } while (0)
; #define PG8_WAIT_V(n) asm volatile("s_waitcnt vmcnt(" #n ")" ::: "memory")
; #define PG8_WAIT_L(n) asm volatile("s_waitcnt lgkmcnt(" #n ")" ::: "memory")
; #define PG8_BAR __builtin_amdgcn_s_barrier()
; #define PG8_SCHED __builtin_amdgcn_sched_barrier(0)
; template <class Epi, class Sched, bool ALIGN_EPI = false, bool SP2 = false>
; __device__ __forceinline__ void gemm_phase(PG8_LAS unsigned char* lds, const Gemm g, const Sched& S, const Epi& E) {
;     ...
;             PG8_LDA(At, 1, 1); PG8_STAGE(PG8_SB(1, 0), b3, voffB); PG8_STAGE(PG8_SB(1, 1), b3 + hstep, voffB); PG8_STAGE(PG8_SA(1, 0), a3, voffA);
;             PG8_WAIT_V(8); PG8_WAIT_L(0); PG8_BAR; PG8_MMA(1, 0, At, B0); PG8_MMA(1, 1, At, B1); PG8_BAR; PG8_SCHED;
;     ...
;         if constexpr (ALIGN_EPI) { if (wr == 0) PG8_BAR; }
	s_add_i32 s28, s56, s2
	v_lshl_add_u64 v[166:167], v[166:167], 0, s[10:11]
	s_mov_b32 m0, s28
	ds_read_b128 v[188:191], v153 offset:49152
	ds_read_b128 v[192:195], v153 offset:50176
	ds_read_b128 v[196:199], v153 offset:51200
	ds_read_b128 v[200:203], v153 offset:52224
	ds_read_b128 v[204:207], v153 offset:53248
	ds_read_b128 v[214:217], v153 offset:54272
	ds_read_b128 v[218:221], v153 offset:55296
	ds_read_b128 v[222:225], v153 offset:56320
	global_load_lds_dwordx4 v[166:167], off
	s_add_i32 m0, s28, 0x2000
	s_add_u32 s26, s26, 0x80080
	v_lshl_add_u64 v[166:167], v[226:227], 0, s[10:11]
	s_addc_u32 s27, s27, 0
	s_add_i32 s28, s57, s2
	global_load_lds_dwordx4 v[166:167], off
	v_lshl_add_u64 v[166:167], s[26:27], 0, v[132:133]
	s_mov_b32 m0, s28
	s_nop 0
	global_load_lds_dwordx4 v[166:167], off
	v_lshl_add_u64 v[166:167], s[26:27], 0, v[128:129]
	s_add_i32 m0, s28, 0x2000
	s_nop 0
	global_load_lds_dwordx4 v[166:167], off
	v_lshl_add_u64 v[166:167], v[228:229], 0, s[10:11]
	s_mov_b32 m0, s37
	s_nop 0
	global_load_lds_dwordx4 v[166:167], off
	v_lshl_add_u64 v[166:167], v[230:231], 0, s[10:11]
	s_mov_b32 m0, s38
	s_nop 0
	global_load_lds_dwordx4 v[166:167], off
	s_waitcnt vmcnt(8)
	s_waitcnt lgkmcnt(0)
	s_barrier
	s_setprio 1
	s_waitcnt lgkmcnt(0)
	v_mfma_f32_16x16x32_bf16 v[60:63], v[144:147], v[188:191], v[60:63]
	v_mfma_f32_16x16x32_bf16 v[52:55], v[158:161], v[188:191], v[52:55]
	v_mfma_f32_16x16x32_bf16 v[44:47], v[144:147], v[196:199], v[44:47]
	v_mfma_f32_16x16x32_bf16 v[36:39], v[158:161], v[196:199], v[36:39]
	v_mfma_f32_16x16x32_bf16 v[28:31], v[144:147], v[204:207], v[28:31]
	v_mfma_f32_16x16x32_bf16 v[20:23], v[158:161], v[204:207], v[20:23]
	v_mfma_f32_16x16x32_bf16 v[12:15], v[144:147], v[218:221], v[12:15]
	v_mfma_f32_16x16x32_bf16 v[4:7], v[158:161], v[218:221], v[4:7]
	v_mfma_f32_16x16x32_bf16 v[60:63], v[154:157], v[192:195], v[60:63]
	v_mfma_f32_16x16x32_bf16 v[52:55], v[162:165], v[192:195], v[52:55]
	v_mfma_f32_16x16x32_bf16 v[44:47], v[154:157], v[200:203], v[44:47]
	v_mfma_f32_16x16x32_bf16 v[36:39], v[162:165], v[200:203], v[36:39]
	v_mfma_f32_16x16x32_bf16 v[28:31], v[154:157], v[214:217], v[28:31]
	v_mfma_f32_16x16x32_bf16 v[20:23], v[162:165], v[214:217], v[20:23]
	v_mfma_f32_16x16x32_bf16 v[12:15], v[154:157], v[222:225], v[12:15]
	v_mfma_f32_16x16x32_bf16 v[4:7], v[162:165], v[222:225], v[4:7]
	s_setprio 0
	s_setprio 1
	v_mfma_f32_16x16x32_bf16 v[56:59], v[172:175], v[188:191], v[56:59]
	v_mfma_f32_16x16x32_bf16 v[48:51], v[180:183], v[188:191], v[48:51]
	v_mfma_f32_16x16x32_bf16 v[40:43], v[172:175], v[196:199], v[40:43]
	v_mfma_f32_16x16x32_bf16 v[32:35], v[180:183], v[196:199], v[32:35]
	v_mfma_f32_16x16x32_bf16 v[24:27], v[172:175], v[204:207], v[24:27]
	v_mfma_f32_16x16x32_bf16 v[16:19], v[180:183], v[204:207], v[16:19]
	v_mfma_f32_16x16x32_bf16 v[8:11], v[172:175], v[218:221], v[8:11]
	v_mfma_f32_16x16x32_bf16 v[0:3], v[180:183], v[218:221], v[0:3]
	v_mfma_f32_16x16x32_bf16 v[56:59], v[176:179], v[192:195], v[56:59]
	v_mfma_f32_16x16x32_bf16 v[48:51], v[184:187], v[192:195], v[48:51]
	v_mfma_f32_16x16x32_bf16 v[40:43], v[176:179], v[200:203], v[40:43]
	v_mfma_f32_16x16x32_bf16 v[32:35], v[184:187], v[200:203], v[32:35]
	v_mfma_f32_16x16x32_bf16 v[24:27], v[176:179], v[214:217], v[24:27]
	v_mfma_f32_16x16x32_bf16 v[16:19], v[184:187], v[214:217], v[16:19]
	v_mfma_f32_16x16x32_bf16 v[8:11], v[176:179], v[222:225], v[8:11]
	v_mfma_f32_16x16x32_bf16 v[0:3], v[184:187], v[222:225], v[0:3]
	s_setprio 0
	s_barrier
	s_add_i32 s55, s55, 2
	s_add_u32 s24, s24, 0x100
	s_addc_u32 s25, s25, 0
	s_add_u32 s53, s53, 0x100
	s_addc_u32 s54, s54, 0
	s_cmp_gt_u32 s55, 29
	s_cbranch_scc0 .LBB0_593
	s_and_b64 vcc, exec, s[12:13]
	s_cbranch_vccz .LBB0_596
	s_barrier

; #define PG8_STAGE(bufoff, gbase, voff) do { _Pragma("unroll") for (int _i = 0; _i < 2; ++_i) \
;         __builtin_amdgcn_global_load_lds((const unsigned*)((const char*)(gbase) + (voff)[_i]), (PG8_LAS unsigned*)(lds + (bufoff) + ldsw + _i * 8192), 16, 0, 0); } while (0)
; #define PG8_LDA(dst, b, h) do { _Pragma("unroll") for (int m = 0; m < 4; ++m) _Pragma("unroll") for (int k = 0; k < 2; ++k) dst[m][k] = *(const PG8_LAS bf16x8*)(lds + PG8_SA(b, h) + aoff + m * 2048 + k * 1024); } while (0)
; #define PG8_LDB(dst, b, h) do { _Pragma("unroll") for (int n = 0; n < 2; ++n) _Pragma("unroll") for (int k = 0; k < 2; ++k) dst[n][k] = *(const PG8_LAS bf16x8*)(lds + PG8_SB(b, h) + boff + n * 2048 + k * 1024); } while (0)
; #define PG8_MMA(ai, bj, At, Bt) do { __builtin_amdgcn_s_setprio(1); _Pragma("unroll") for (int m = 0; m < 4; ++m) _Pragma("unroll") for (int n = 0; n < 2; ++n) _Pragma("unroll") for (int k = 0; k < 2; ++k) \
;         acc[ai][bj][m][n] = __builtin_amdgcn_mfma_f32_16x16x32_bf16(Bt[n][k], At[m][k], acc[ai][bj][m][n], 0, 0, 0); __builtin_amdgcn_s_setprio(0); } while (0)
; #define PG8_WAIT_V(n) asm volatile("s_waitcnt vmcnt(" #n ")" ::: "memory")
; #define PG8_WAIT_L(n) asm volatile("s_waitcnt lgkmcnt(" #n ")" ::: "memory")
; #define PG8_BAR __builtin_amdgcn_s_barrier()
; #define PG8_SCHED __builtin_amdgcn_sched_barrier(0)
; template <class Epi, class Sched, bool ALIGN_EPI = false, bool SP2 = false>
; __device__ __forceinline__ void gemm_phase(PG8_LAS unsigned char* lds, const Gemm g, const Sched& S, const Epi& E) {
;     ...
;             PG8_LDB(B0, 0, 0); PG8_LDB(B1, 0, 1); PG8_SCHED; PG8_LDA(At, 0, 0); PG8_STAGE(PG8_SA(1, 1), a1 + hstep, voffA);
;             PG8_WAIT_V(8); PG8_WAIT_L(0); PG8_BAR; PG8_MMA(0, 0, At, B0); PG8_MMA(0, 1, At, B1); PG8_BAR; PG8_SCHED;
;             PG8_LDA(At, 0, 1); PG8_STAGE(PG8_SB(0, 0), b2, voffB); PG8_STAGE(PG8_SB(0, 1), b2 + hstep, voffB); PG8_STAGE(PG8_SA(0, 0), a2, voffA);
;             PG8_WAIT_V(8); PG8_WAIT_L(0); PG8_BAR; PG8_MMA(1, 0, At, B0); PG8_MMA(1, 1, At, B1); PG8_BAR; PG8_SCHED;
.LBB0_659:
	ds_read_b128 v[120:123], v168
	ds_read_b128 v[124:127], v168 offset:1024
	ds_read_b128 v[136:139], v168 offset:2048
	ds_read_b128 v[140:143], v168 offset:3072
	ds_read_b128 v[162:165], v169
	ds_read_b128 v[174:177], v169 offset:1024
	ds_read_b128 v[178:181], v169 offset:2048
	ds_read_b128 v[182:185], v169 offset:3072
	s_add_u32 s22, s4, 0xffea0080
	s_addc_u32 s23, s5, -1
	s_cmpk_eq_i32 s46, 0x54
	s_cselect_b32 s25, s19, s23
	s_cselect_b32 s24, s18, s22
	s_cselect_b32 s23, s7, s21
	s_cselect_b32 s22, s6, s20
	v_lshl_add_u64 v[218:219], s[4:5], 0, v[158:159]
	s_add_i32 m0, s28, 0xc000
	ds_read_b128 v[186:189], v170
	ds_read_b128 v[190:193], v170 offset:1024
	ds_read_b128 v[194:197], v170 offset:2048
	ds_read_b128 v[198:201], v170 offset:3072
	ds_read_b128 v[202:205], v170 offset:4096
	ds_read_b128 v[206:209], v170 offset:5120
	ds_read_b128 v[210:213], v170 offset:6144
	ds_read_b128 v[214:217], v170 offset:7168
	global_load_lds_dwordx4 v[218:219], off
	v_lshl_add_u64 v[218:219], s[4:5], 0, v[160:161]
	s_add_i32 m0, s28, 0xe000
	s_nop 0
	global_load_lds_dwordx4 v[218:219], off
	s_waitcnt vmcnt(8)
	s_waitcnt lgkmcnt(0)
	s_barrier
	s_setprio 1
	s_waitcnt lgkmcnt(0)
	v_mfma_f32_16x16x32_bf16 v[132:135], v[120:123], v[186:189], v[132:135]
	v_mfma_f32_16x16x32_bf16 v[128:131], v[136:139], v[186:189], v[128:131]
	v_mfma_f32_16x16x32_bf16 v[108:111], v[120:123], v[194:197], v[108:111]
	v_mfma_f32_16x16x32_bf16 v[104:107], v[136:139], v[194:197], v[104:107]
	v_mfma_f32_16x16x32_bf16 v[92:95], v[120:123], v[202:205], v[92:95]
	v_mfma_f32_16x16x32_bf16 v[88:91], v[136:139], v[202:205], v[88:91]
	v_mfma_f32_16x16x32_bf16 v[76:79], v[120:123], v[210:213], v[76:79]
	v_mfma_f32_16x16x32_bf16 v[72:75], v[136:139], v[210:213], v[72:75]
	v_mfma_f32_16x16x32_bf16 v[132:135], v[124:127], v[190:193], v[132:135]
	v_mfma_f32_16x16x32_bf16 v[128:131], v[140:143], v[190:193], v[128:131]
	v_mfma_f32_16x16x32_bf16 v[108:111], v[124:127], v[198:201], v[108:111]
	v_mfma_f32_16x16x32_bf16 v[104:107], v[140:143], v[198:201], v[104:107]
	v_mfma_f32_16x16x32_bf16 v[92:95], v[124:127], v[206:209], v[92:95]
	v_mfma_f32_16x16x32_bf16 v[88:91], v[140:143], v[206:209], v[88:91]
	v_mfma_f32_16x16x32_bf16 v[76:79], v[124:127], v[214:217], v[76:79]
	v_mfma_f32_16x16x32_bf16 v[72:75], v[140:143], v[214:217], v[72:75]
	s_setprio 0
	s_setprio 1
	v_mfma_f32_16x16x32_bf16 v[116:119], v[162:165], v[186:189], v[116:119]
	v_mfma_f32_16x16x32_bf16 v[112:115], v[178:181], v[186:189], v[112:115]
	v_mfma_f32_16x16x32_bf16 v[100:103], v[162:165], v[194:197], v[100:103]
	v_mfma_f32_16x16x32_bf16 v[96:99], v[178:181], v[194:197], v[96:99]
	v_mfma_f32_16x16x32_bf16 v[84:87], v[162:165], v[202:205], v[84:87]
	v_mfma_f32_16x16x32_bf16 v[80:83], v[178:181], v[202:205], v[80:83]
	v_mfma_f32_16x16x32_bf16 v[68:71], v[162:165], v[210:213], v[68:71]
	v_mfma_f32_16x16x32_bf16 v[64:67], v[178:181], v[210:213], v[64:67]
	v_mfma_f32_16x16x32_bf16 v[116:119], v[174:177], v[190:193], v[116:119]
	v_mfma_f32_16x16x32_bf16 v[112:115], v[182:185], v[190:193], v[112:115]
	v_mfma_f32_16x16x32_bf16 v[100:103], v[174:177], v[198:201], v[100:103]
	v_mfma_f32_16x16x32_bf16 v[96:99], v[182:185], v[198:201], v[96:99]
	v_mfma_f32_16x16x32_bf16 v[84:87], v[174:177], v[206:209], v[84:87]
	v_mfma_f32_16x16x32_bf16 v[80:83], v[182:185], v[206:209], v[80:83]
	v_mfma_f32_16x16x32_bf16 v[68:71], v[174:177], v[214:217], v[68:71]
	v_mfma_f32_16x16x32_bf16 v[64:67], v[182:185], v[214:217], v[64:67]
	s_setprio 0
	s_barrier
	s_add_i32 s47, s38, s26
	v_lshl_add_u64 v[218:219], s[22:23], 0, v[148:149]
	s_mov_b32 m0, s47
	ds_read_b128 v[186:189], v170 offset:16384
	ds_read_b128 v[190:193], v170 offset:17408
	ds_read_b128 v[194:197], v170 offset:18432
	ds_read_b128 v[198:201], v170 offset:19456
	ds_read_b128 v[202:205], v170 offset:20480
	ds_read_b128 v[206:209], v170 offset:21504
	ds_read_b128 v[210:213], v170 offset:22528
	ds_read_b128 v[214:217], v170 offset:23552
	global_load_lds_dwordx4 v[218:219], off
	s_add_i32 m0, s47, 0x2000
	s_add_u32 s48, s22, 0x160000
	v_lshl_add_u64 v[220:221], s[22:23], 0, v[144:145]
	s_addc_u32 s49, s23, 0
	s_add_i32 s47, s39, s26
	global_load_lds_dwordx4 v[220:221], off
	v_lshl_add_u64 v[222:223], s[48:49], 0, v[148:149]
	s_mov_b32 m0, s47
	v_lshl_add_u64 v[224:225], s[24:25], 0, v[146:147]
	global_load_lds_dwordx4 v[222:223], off
	v_lshl_add_u64 v[222:223], s[48:49], 0, v[144:145]
	s_add_i32 m0, s47, 0x2000
	s_nop 0
	global_load_lds_dwordx4 v[222:223], off
	s_waitcnt vmcnt(6)
	s_waitcnt lgkmcnt(0)
	s_barrier
; #define PG8_STAGE(bufoff, gbase, voff) do { _Pragma("unroll") for (int _i = 0; _i < 2; ++_i) \
;         __builtin_amdgcn_global_load_lds((const unsigned*)((const char*)(gbase) + (voff)[_i]), (PG8_LAS unsigned*)(lds + (bufoff) + ldsw + _i * 8192), 16, 0, 0); } while (0)
; #define PG8_LDA(dst, b, h) do { _Pragma("unroll") for (int m = 0; m < 4; ++m) _Pragma("unroll") for (int k = 0; k < 2; ++k) dst[m][k] = *(const PG8_LAS bf16x8*)(lds + PG8_SA(b, h) + aoff + m * 2048 + k * 1024); } while (0)
; #define PG8_LDB(dst, b, h) do { _Pragma("unroll") for (int n = 0; n < 2; ++n) _Pragma("unroll") for (int k = 0; k < 2; ++k) dst[n][k] = *(const PG8_LAS bf16x8*)(lds + PG8_SB(b, h) + boff + n * 2048 + k * 1024); } while (0)
; #define PG8_MMA(ai, bj, At, Bt) do { __builtin_amdgcn_s_setprio(1); _Pragma("unroll") for (int m = 0; m < 4; ++m) _Pragma("unroll") for (int n = 0; n < 2; ++n) _Pragma("unroll") for (int k = 0; k < 2; ++k) \
;         acc[ai][bj][m][n] = __builtin_amdgcn_mfma_f32_16x16x32_bf16(Bt[n][k], At[m][k], acc[ai][bj][m][n], 0, 0, 0); __builtin_amdgcn_s_setprio(0); } while (0)
; #define PG8_WAIT_V(n) asm volatile("s_waitcnt vmcnt(" #n ")" ::: "memory")
; #define PG8_WAIT_L(n) asm volatile("s_waitcnt lgkmcnt(" #n ")" ::: "memory")
; #define PG8_BAR __builtin_amdgcn_s_barrier()
; #define PG8_SCHED __builtin_amdgcn_sched_barrier(0)
; template <class Epi, class Sched, bool ALIGN_EPI = false, bool SP2 = false>
; __device__ __forceinline__ void gemm_phase(PG8_LAS unsigned char* lds, const Gemm g, const Sched& S, const Epi& E) {
;     ...
;             PG8_WAIT_V(8); PG8_WAIT_L(0); PG8_BAR; PG8_MMA(1, 0, At, B0); PG8_MMA(1, 1, At, B1); PG8_BAR; PG8_SCHED;
;             PG8_LDB(B0, 1, 0); PG8_LDB(B1, 1, 1); PG8_SCHED; PG8_LDA(At, 1, 0); PG8_STAGE(PG8_SA(0, 1), a2 + hstep, voffA);
;             PG8_WAIT_V(8); PG8_WAIT_L(0); PG8_BAR; PG8_MMA(0, 0, At, B0); PG8_MMA(0, 1, At, B1); PG8_BAR; PG8_SCHED;
	s_setprio 1
	s_waitcnt lgkmcnt(0)
	v_mfma_f32_16x16x32_bf16 v[60:63], v[120:123], v[186:189], v[60:63]
	v_mfma_f32_16x16x32_bf16 v[56:59], v[136:139], v[186:189], v[56:59]
	v_mfma_f32_16x16x32_bf16 v[44:47], v[120:123], v[194:197], v[44:47]
	v_mfma_f32_16x16x32_bf16 v[40:43], v[136:139], v[194:197], v[40:43]
	v_mfma_f32_16x16x32_bf16 v[28:31], v[120:123], v[202:205], v[28:31]
	v_mfma_f32_16x16x32_bf16 v[24:27], v[136:139], v[202:205], v[24:27]
	v_mfma_f32_16x16x32_bf16 v[12:15], v[120:123], v[210:213], v[12:15]
	v_mfma_f32_16x16x32_bf16 v[8:11], v[136:139], v[210:213], v[8:11]
	v_mfma_f32_16x16x32_bf16 v[60:63], v[124:127], v[190:193], v[60:63]
	v_mfma_f32_16x16x32_bf16 v[56:59], v[140:143], v[190:193], v[56:59]
	v_mfma_f32_16x16x32_bf16 v[44:47], v[124:127], v[198:201], v[44:47]
	v_mfma_f32_16x16x32_bf16 v[40:43], v[140:143], v[198:201], v[40:43]
	v_mfma_f32_16x16x32_bf16 v[28:31], v[124:127], v[206:209], v[28:31]
	v_mfma_f32_16x16x32_bf16 v[24:27], v[140:143], v[206:209], v[24:27]
	v_mfma_f32_16x16x32_bf16 v[12:15], v[124:127], v[214:217], v[12:15]
	v_mfma_f32_16x16x32_bf16 v[8:11], v[140:143], v[214:217], v[8:11]
	s_setprio 0
	s_setprio 1
	v_mfma_f32_16x16x32_bf16 v[52:55], v[162:165], v[186:189], v[52:55]
	v_mfma_f32_16x16x32_bf16 v[48:51], v[178:181], v[186:189], v[48:51]
	v_mfma_f32_16x16x32_bf16 v[36:39], v[162:165], v[194:197], v[36:39]
	v_mfma_f32_16x16x32_bf16 v[32:35], v[178:181], v[194:197], v[32:35]
	v_mfma_f32_16x16x32_bf16 v[20:23], v[162:165], v[202:205], v[20:23]
	v_mfma_f32_16x16x32_bf16 v[16:19], v[178:181], v[202:205], v[16:19]
	v_mfma_f32_16x16x32_bf16 v[4:7], v[162:165], v[210:213], v[4:7]
	v_mfma_f32_16x16x32_bf16 v[0:3], v[178:181], v[210:213], v[0:3]
	v_mfma_f32_16x16x32_bf16 v[52:55], v[174:177], v[190:193], v[52:55]
	v_mfma_f32_16x16x32_bf16 v[48:51], v[182:185], v[190:193], v[48:51]
	v_mfma_f32_16x16x32_bf16 v[36:39], v[174:177], v[198:201], v[36:39]
	v_mfma_f32_16x16x32_bf16 v[32:35], v[182:185], v[198:201], v[32:35]
	v_mfma_f32_16x16x32_bf16 v[20:23], v[174:177], v[206:209], v[20:23]
	v_mfma_f32_16x16x32_bf16 v[16:19], v[182:185], v[206:209], v[16:19]
	v_mfma_f32_16x16x32_bf16 v[4:7], v[174:177], v[214:217], v[4:7]
	v_mfma_f32_16x16x32_bf16 v[0:3], v[182:185], v[214:217], v[0:3]
	s_setprio 0
	s_barrier
	s_add_i32 s47, 0, 0x18000
	s_add_i32 s48, 0, 0x1c000
	v_add_u32_e32 v140, s47, v167
	v_add_u32_e32 v182, s48, v167
	ds_read_b128 v[120:123], v140
	ds_read_b128 v[124:127], v140 offset:1024
	ds_read_b128 v[136:139], v140 offset:2048
	ds_read_b128 v[140:143], v140 offset:3072
	ds_read_b128 v[162:165], v182
	ds_read_b128 v[174:177], v182 offset:1024
	ds_read_b128 v[178:181], v182 offset:2048
	ds_read_b128 v[182:185], v182 offset:3072
	v_lshl_add_u64 v[222:223], s[24:25], 0, v[150:151]
	s_mov_b32 m0, s28
	s_nop 0
	global_load_lds_dwordx4 v[222:223], off
	s_mov_b32 m0, s29
	s_nop 0
	global_load_lds_dwordx4 v[224:225], off
	s_add_u32 s24, s24, 0x160000
	s_addc_u32 s25, s25, 0
	s_mov_b32 m0, s30
	v_lshl_add_u64 v[226:227], s[24:25], 0, v[150:151]
	ds_read_b128 v[186:189], v170 offset:32768
	ds_read_b128 v[190:193], v170 offset:33792
	ds_read_b128 v[194:197], v170 offset:34816
	ds_read_b128 v[198:201], v170 offset:35840
	ds_read_b128 v[202:205], v170 offset:36864
	ds_read_b128 v[206:209], v170 offset:37888
	ds_read_b128 v[210:213], v170 offset:38912
	ds_read_b128 v[214:217], v170 offset:39936
	global_load_lds_dwordx4 v[226:227], off
	v_lshl_add_u64 v[226:227], s[24:25], 0, v[146:147]
	s_mov_b32 m0, s31
	s_nop 0
	global_load_lds_dwordx4 v[226:227], off
	s_waitcnt vmcnt(8)
	s_waitcnt lgkmcnt(0)
	s_barrier
	s_setprio 1
	s_waitcnt lgkmcnt(0)
	v_mfma_f32_16x16x32_bf16 v[132:135], v[120:123], v[186:189], v[132:135]
	v_mfma_f32_16x16x32_bf16 v[128:131], v[136:139], v[186:189], v[128:131]
	v_mfma_f32_16x16x32_bf16 v[108:111], v[120:123], v[194:197], v[108:111]
	v_mfma_f32_16x16x32_bf16 v[104:107], v[136:139], v[194:197], v[104:107]
	v_mfma_f32_16x16x32_bf16 v[92:95], v[120:123], v[202:205], v[92:95]
	v_mfma_f32_16x16x32_bf16 v[88:91], v[136:139], v[202:205], v[88:91]
	v_mfma_f32_16x16x32_bf16 v[76:79], v[120:123], v[210:213], v[76:79]
	v_mfma_f32_16x16x32_bf16 v[72:75], v[136:139], v[210:213], v[72:75]
	v_mfma_f32_16x16x32_bf16 v[132:135], v[124:127], v[190:193], v[132:135]
	v_mfma_f32_16x16x32_bf16 v[128:131], v[140:143], v[190:193], v[128:131]
	v_mfma_f32_16x16x32_bf16 v[108:111], v[124:127], v[198:201], v[108:111]
	v_mfma_f32_16x16x32_bf16 v[104:107], v[140:143], v[198:201], v[104:107]
	v_mfma_f32_16x16x32_bf16 v[92:95], v[124:127], v[206:209], v[92:95]
	v_mfma_f32_16x16x32_bf16 v[88:91], v[140:143], v[206:209], v[88:91]
	v_mfma_f32_16x16x32_bf16 v[76:79], v[124:127], v[214:217], v[76:79]
	v_mfma_f32_16x16x32_bf16 v[72:75], v[140:143], v[214:217], v[72:75]
	s_setprio 0
	s_setprio 1
	v_mfma_f32_16x16x32_bf16 v[116:119], v[162:165], v[186:189], v[116:119]
	v_mfma_f32_16x16x32_bf16 v[112:115], v[178:181], v[186:189], v[112:115]
	v_mfma_f32_16x16x32_bf16 v[100:103], v[162:165], v[194:197], v[100:103]
	v_mfma_f32_16x16x32_bf16 v[96:99], v[178:181], v[194:197], v[96:99]
	v_mfma_f32_16x16x32_bf16 v[84:87], v[162:165], v[202:205], v[84:87]
	v_mfma_f32_16x16x32_bf16 v[80:83], v[178:181], v[202:205], v[80:83]
	v_mfma_f32_16x16x32_bf16 v[68:71], v[162:165], v[210:213], v[68:71]
	v_mfma_f32_16x16x32_bf16 v[64:67], v[178:181], v[210:213], v[64:67]
	v_mfma_f32_16x16x32_bf16 v[116:119], v[174:177], v[190:193], v[116:119]
	v_mfma_f32_16x16x32_bf16 v[112:115], v[182:185], v[190:193], v[112:115]
	v_mfma_f32_16x16x32_bf16 v[100:103], v[174:177], v[198:201], v[100:103]
	v_mfma_f32_16x16x32_bf16 v[96:99], v[182:185], v[198:201], v[96:99]
	v_mfma_f32_16x16x32_bf16 v[84:87], v[174:177], v[206:209], v[84:87]
	v_mfma_f32_16x16x32_bf16 v[80:83], v[182:185], v[206:209], v[80:83]
	v_mfma_f32_16x16x32_bf16 v[68:71], v[174:177], v[214:217], v[68:71]
	v_mfma_f32_16x16x32_bf16 v[64:67], v[182:185], v[214:217], v[64:67]
	s_setprio 0
	s_barrier
; #define PG8_STAGE(bufoff, gbase, voff) do { _Pragma("unroll") for (int _i = 0; _i < 2; ++_i) \
;         __builtin_amdgcn_global_load_lds((const unsigned*)((const char*)(gbase) + (voff)[_i]), (PG8_LAS unsigned*)(lds + (bufoff) + ldsw + _i * 8192), 16, 0, 0); } while (0)
; #define PG8_LDA(dst, b, h) do { _Pragma("unroll") for (int m = 0; m < 4; ++m) _Pragma("unroll") for (int k = 0; k < 2; ++k) dst[m][k] = *(const PG8_LAS bf16x8*)(lds + PG8_SA(b, h) + aoff + m * 2048 + k * 1024); } while (0)
; #define PG8_MMA(ai, bj, At, Bt) do { __builtin_amdgcn_s_setprio(1); _Pragma("unroll") for (int m = 0; m < 4; ++m) _Pragma("unroll") for (int n = 0; n < 2; ++n) _Pragma("unroll") for (int k = 0; k < 2; ++k) \
;         acc[ai][bj][m][n] = __builtin_amdgcn_mfma_f32_16x16x32_bf16(Bt[n][k], At[m][k], acc[ai][bj][m][n], 0, 0, 0); __builtin_amdgcn_s_setprio(0); } while (0)
; #define PG8_WAIT_V(n) asm volatile("s_waitcnt vmcnt(" #n ")" ::: "memory")
; #define PG8_WAIT_L(n) asm volatile("s_waitcnt lgkmcnt(" #n ")" ::: "memory")
; #define PG8_BAR __builtin_amdgcn_s_barrier()
; #define PG8_SCHED __builtin_amdgcn_sched_barrier(0)
; template <class Epi, class Sched, bool ALIGN_EPI = false, bool SP2 = false>
; __device__ __forceinline__ void gemm_phase(PG8_LAS unsigned char* lds, const Gemm g, const Sched& S, const Epi& E) {
;     ...
;             PG8_LDA(At, 1, 1); PG8_STAGE(PG8_SB(1, 0), b3, voffB); PG8_STAGE(PG8_SB(1, 1), b3 + hstep, voffB); PG8_STAGE(PG8_SA(1, 0), a3, voffA);
;             PG8_WAIT_V(8); PG8_WAIT_L(0); PG8_BAR; PG8_MMA(1, 0, At, B0); PG8_MMA(1, 1, At, B1); PG8_BAR; PG8_SCHED;
;     ...
;         if constexpr (ALIGN_EPI) { if (wr == 0) PG8_BAR; }
	s_add_i32 s24, s47, s26
	v_lshl_add_u64 v[218:219], v[218:219], 0, s[12:13]
	s_mov_b32 m0, s24
	ds_read_b128 v[186:189], v170 offset:49152
	ds_read_b128 v[190:193], v170 offset:50176
	ds_read_b128 v[194:197], v170 offset:51200
	ds_read_b128 v[198:201], v170 offset:52224
	ds_read_b128 v[202:205], v170 offset:53248
	ds_read_b128 v[206:209], v170 offset:54272
	ds_read_b128 v[210:213], v170 offset:55296
	ds_read_b128 v[214:217], v170 offset:56320
	global_load_lds_dwordx4 v[218:219], off
	s_add_i32 m0, s24, 0x2000
	s_add_u32 s22, s22, 0x160080
	v_lshl_add_u64 v[218:219], v[220:221], 0, s[12:13]
	s_addc_u32 s23, s23, 0
	s_add_i32 s24, s48, s26
	global_load_lds_dwordx4 v[218:219], off
	v_lshl_add_u64 v[218:219], s[22:23], 0, v[148:149]
	s_mov_b32 m0, s24
	s_nop 0
	global_load_lds_dwordx4 v[218:219], off
	v_lshl_add_u64 v[218:219], s[22:23], 0, v[144:145]
	s_add_i32 m0, s24, 0x2000
	s_nop 0
	global_load_lds_dwordx4 v[218:219], off
	v_lshl_add_u64 v[218:219], v[222:223], 0, s[12:13]
	s_mov_b32 m0, s36
	s_nop 0
	global_load_lds_dwordx4 v[218:219], off
	v_lshl_add_u64 v[218:219], v[224:225], 0, s[12:13]
	s_mov_b32 m0, s37
	s_nop 0
	global_load_lds_dwordx4 v[218:219], off
	s_waitcnt vmcnt(8)
	s_waitcnt lgkmcnt(0)
	s_barrier
	s_setprio 1
	s_waitcnt lgkmcnt(0)
	v_mfma_f32_16x16x32_bf16 v[60:63], v[120:123], v[186:189], v[60:63]
	v_mfma_f32_16x16x32_bf16 v[56:59], v[136:139], v[186:189], v[56:59]
	v_mfma_f32_16x16x32_bf16 v[44:47], v[120:123], v[194:197], v[44:47]
	v_mfma_f32_16x16x32_bf16 v[40:43], v[136:139], v[194:197], v[40:43]
	v_mfma_f32_16x16x32_bf16 v[28:31], v[120:123], v[202:205], v[28:31]
	v_mfma_f32_16x16x32_bf16 v[24:27], v[136:139], v[202:205], v[24:27]
	v_mfma_f32_16x16x32_bf16 v[12:15], v[120:123], v[210:213], v[12:15]
	v_mfma_f32_16x16x32_bf16 v[8:11], v[136:139], v[210:213], v[8:11]
	v_mfma_f32_16x16x32_bf16 v[60:63], v[124:127], v[190:193], v[60:63]
	v_mfma_f32_16x16x32_bf16 v[56:59], v[140:143], v[190:193], v[56:59]
	v_mfma_f32_16x16x32_bf16 v[44:47], v[124:127], v[198:201], v[44:47]
	v_mfma_f32_16x16x32_bf16 v[40:43], v[140:143], v[198:201], v[40:43]
	v_mfma_f32_16x16x32_bf16 v[28:31], v[124:127], v[206:209], v[28:31]
	v_mfma_f32_16x16x32_bf16 v[24:27], v[140:143], v[206:209], v[24:27]
	v_mfma_f32_16x16x32_bf16 v[12:15], v[124:127], v[214:217], v[12:15]
	v_mfma_f32_16x16x32_bf16 v[8:11], v[140:143], v[214:217], v[8:11]
	s_setprio 0
	s_setprio 1
	v_mfma_f32_16x16x32_bf16 v[52:55], v[162:165], v[186:189], v[52:55]
	v_mfma_f32_16x16x32_bf16 v[48:51], v[178:181], v[186:189], v[48:51]
	v_mfma_f32_16x16x32_bf16 v[36:39], v[162:165], v[194:197], v[36:39]
	v_mfma_f32_16x16x32_bf16 v[32:35], v[178:181], v[194:197], v[32:35]
	v_mfma_f32_16x16x32_bf16 v[20:23], v[162:165], v[202:205], v[20:23]
	v_mfma_f32_16x16x32_bf16 v[16:19], v[178:181], v[202:205], v[16:19]
	v_mfma_f32_16x16x32_bf16 v[4:7], v[162:165], v[210:213], v[4:7]
	v_mfma_f32_16x16x32_bf16 v[0:3], v[178:181], v[210:213], v[0:3]
	v_mfma_f32_16x16x32_bf16 v[52:55], v[174:177], v[190:193], v[52:55]
	v_mfma_f32_16x16x32_bf16 v[48:51], v[182:185], v[190:193], v[48:51]
	v_mfma_f32_16x16x32_bf16 v[36:39], v[174:177], v[198:201], v[36:39]
	v_mfma_f32_16x16x32_bf16 v[32:35], v[182:185], v[198:201], v[32:35]
	v_mfma_f32_16x16x32_bf16 v[20:23], v[174:177], v[206:209], v[20:23]
	v_mfma_f32_16x16x32_bf16 v[16:19], v[182:185], v[206:209], v[16:19]
	v_mfma_f32_16x16x32_bf16 v[4:7], v[174:177], v[214:217], v[4:7]
	v_mfma_f32_16x16x32_bf16 v[0:3], v[182:185], v[214:217], v[0:3]
	s_setprio 0
	s_barrier
	s_add_i32 s46, s46, 2
	s_add_u32 s4, s4, 0x100
	s_addc_u32 s5, s5, 0
	s_add_u32 s20, s20, 0x100
	s_addc_u32 s21, s21, 0
	s_cmpk_gt_u32 s46, 0x55
	s_cbranch_scc0 .LBB0_659
	s_and_b64 vcc, exec, s[14:15]
	s_cbranch_vccz .LBB0_662
	s_barrier
